# v9 + all ten GEMM K-loops: the two A-tile DMA pieces of SP2(t) issued one load segment later (2/4/4/6 pieces instead of 2/6/2/6), wait vmcnt(6) there
# speedup vs baseline: 1.0035x; 1.0013x over previous
.LBB0_241:
	ds_read_b128 v[136:139], v174
	ds_read_b128 v[140:143], v174 offset:1024
	ds_read_b128 v[178:181], v174 offset:2048
	ds_read_b128 v[186:189], v174 offset:3072
	ds_read_b128 v[190:193], v175
	ds_read_b128 v[194:197], v175 offset:1024
	ds_read_b128 v[198:201], v175 offset:2048
	ds_read_b128 v[202:205], v175 offset:3072
	s_cmp_eq_u32 s23, 12
	v_lshl_add_u64 v[170:171], v[132:133], 0, s[20:21]
	s_cselect_b64 vcc, -1, 0
	v_cndmask_b32_e32 v171, v171, v129, vcc
	v_cndmask_b32_e32 v170, v170, v128, vcc
	v_cndmask_b32_e32 v183, v135, v131, vcc
	v_cndmask_b32_e32 v182, v134, v130, vcc
	s_mov_b32 m0, s50
	v_lshl_add_u64 v[240:241], v[132:133], 0, v[152:153]
	ds_read_b128 v[206:209], v176
	ds_read_b128 v[210:213], v176 offset:1024
	ds_read_b128 v[214:217], v176 offset:2048
	ds_read_b128 v[218:221], v176 offset:3072
	ds_read_b128 v[222:225], v176 offset:4096
	ds_read_b128 v[226:229], v176 offset:5120
	ds_read_b128 v[230:233], v176 offset:6144
	ds_read_b128 v[236:239], v176 offset:7168
	global_load_lds_dwordx4 v[240:241], off
	v_lshl_add_u64 v[240:241], v[132:133], 0, v[154:155]
	s_mov_b32 m0, s51
	s_nop 0
	global_load_lds_dwordx4 v[240:241], off
	s_waitcnt vmcnt(8)
	s_waitcnt lgkmcnt(0)
	s_barrier
	s_setprio 1
	s_waitcnt lgkmcnt(0)
	v_mfma_f32_16x16x32_bf16 v[124:127], v[136:139], v[206:209], v[124:127]
	v_mfma_f32_16x16x32_bf16 v[120:123], v[178:181], v[206:209], v[120:123]
	v_mfma_f32_16x16x32_bf16 v[116:119], v[136:139], v[214:217], v[116:119]
	v_mfma_f32_16x16x32_bf16 v[112:115], v[178:181], v[214:217], v[112:115]
	v_mfma_f32_16x16x32_bf16 v[108:111], v[136:139], v[222:225], v[108:111]
	v_mfma_f32_16x16x32_bf16 v[96:99], v[178:181], v[222:225], v[96:99]
	v_mfma_f32_16x16x32_bf16 v[84:87], v[136:139], v[230:233], v[84:87]
	v_mfma_f32_16x16x32_bf16 v[76:79], v[178:181], v[230:233], v[76:79]
	v_mfma_f32_16x16x32_bf16 v[124:127], v[140:143], v[210:213], v[124:127]
	v_mfma_f32_16x16x32_bf16 v[120:123], v[186:189], v[210:213], v[120:123]
	v_mfma_f32_16x16x32_bf16 v[116:119], v[140:143], v[218:221], v[116:119]
	v_mfma_f32_16x16x32_bf16 v[112:115], v[186:189], v[218:221], v[112:115]
	v_mfma_f32_16x16x32_bf16 v[108:111], v[140:143], v[226:229], v[108:111]
	v_mfma_f32_16x16x32_bf16 v[96:99], v[186:189], v[226:229], v[96:99]
	v_mfma_f32_16x16x32_bf16 v[84:87], v[140:143], v[236:239], v[84:87]
	v_mfma_f32_16x16x32_bf16 v[76:79], v[186:189], v[236:239], v[76:79]
	s_setprio 0
	s_setprio 1
	v_mfma_f32_16x16x32_bf16 v[104:107], v[190:193], v[206:209], v[104:107]
	v_mfma_f32_16x16x32_bf16 v[100:103], v[198:201], v[206:209], v[100:103]
	v_mfma_f32_16x16x32_bf16 v[92:95], v[190:193], v[214:217], v[92:95]
	v_mfma_f32_16x16x32_bf16 v[88:91], v[198:201], v[214:217], v[88:91]
	v_mfma_f32_16x16x32_bf16 v[80:83], v[190:193], v[222:225], v[80:83]
	v_mfma_f32_16x16x32_bf16 v[72:75], v[198:201], v[222:225], v[72:75]
	v_mfma_f32_16x16x32_bf16 v[68:71], v[190:193], v[230:233], v[68:71]
	v_mfma_f32_16x16x32_bf16 v[64:67], v[198:201], v[230:233], v[64:67]
	v_mfma_f32_16x16x32_bf16 v[104:107], v[194:197], v[210:213], v[104:107]
	v_mfma_f32_16x16x32_bf16 v[100:103], v[202:205], v[210:213], v[100:103]
	v_mfma_f32_16x16x32_bf16 v[92:95], v[194:197], v[218:221], v[92:95]
	v_mfma_f32_16x16x32_bf16 v[88:91], v[202:205], v[218:221], v[88:91]
	v_mfma_f32_16x16x32_bf16 v[80:83], v[194:197], v[226:229], v[80:83]
	v_mfma_f32_16x16x32_bf16 v[72:75], v[202:205], v[226:229], v[72:75]
	v_mfma_f32_16x16x32_bf16 v[68:71], v[194:197], v[236:239], v[68:71]
	v_mfma_f32_16x16x32_bf16 v[64:67], v[202:205], v[236:239], v[64:67]
	s_setprio 0
	s_barrier
	s_mov_b32 m0, s53
	v_lshl_add_u64 v[240:241], v[182:183], 0, v[148:149]
	ds_read_b128 v[206:209], v176 offset:16384
	ds_read_b128 v[210:213], v176 offset:17408
	ds_read_b128 v[214:217], v176 offset:18432
	ds_read_b128 v[218:221], v176 offset:19456
	ds_read_b128 v[222:225], v176 offset:20480
	ds_read_b128 v[226:229], v176 offset:21504
	ds_read_b128 v[230:233], v176 offset:22528
	ds_read_b128 v[236:239], v176 offset:23552
	global_load_lds_dwordx4 v[240:241], off
	v_lshl_add_u64 v[242:243], v[182:183], 0, v[144:145]
	s_mov_b32 m0, s54
	v_lshl_add_u64 v[244:245], v[182:183], 0, s[6:7]
	s_add_i32 s25, s49, s33
	global_load_lds_dwordx4 v[242:243], off
	v_lshl_add_u64 v[246:247], v[244:245], 0, v[148:149]
	s_mov_b32 m0, s25
	v_lshl_add_u64 v[244:245], v[244:245], 0, v[144:145]
	global_load_lds_dwordx4 v[246:247], off
	s_add_i32 m0, s25, 0x2000
	v_lshl_add_u64 v[246:247], v[170:171], 0, v[146:147]
	global_load_lds_dwordx4 v[244:245], off
	v_lshl_add_u64 v[244:245], v[170:171], 0, v[150:151]
	s_waitcnt vmcnt(6)
	s_waitcnt lgkmcnt(0)
	s_barrier
	s_setprio 1
	s_waitcnt lgkmcnt(0)
	v_mfma_f32_16x16x32_bf16 v[60:63], v[136:139], v[206:209], v[60:63]
	v_mfma_f32_16x16x32_bf16 v[56:59], v[178:181], v[206:209], v[56:59]
	v_mfma_f32_16x16x32_bf16 v[52:55], v[136:139], v[214:217], v[52:55]
	v_mfma_f32_16x16x32_bf16 v[44:47], v[178:181], v[214:217], v[44:47]
	v_mfma_f32_16x16x32_bf16 v[36:39], v[136:139], v[222:225], v[36:39]
	v_mfma_f32_16x16x32_bf16 v[28:31], v[178:181], v[222:225], v[28:31]
	v_mfma_f32_16x16x32_bf16 v[20:23], v[136:139], v[230:233], v[20:23]
	v_mfma_f32_16x16x32_bf16 v[12:15], v[178:181], v[230:233], v[12:15]
	v_mfma_f32_16x16x32_bf16 v[60:63], v[140:143], v[210:213], v[60:63]
	v_mfma_f32_16x16x32_bf16 v[56:59], v[186:189], v[210:213], v[56:59]
	v_mfma_f32_16x16x32_bf16 v[52:55], v[140:143], v[218:221], v[52:55]
	v_mfma_f32_16x16x32_bf16 v[44:47], v[186:189], v[218:221], v[44:47]
	v_mfma_f32_16x16x32_bf16 v[36:39], v[140:143], v[226:229], v[36:39]
	v_mfma_f32_16x16x32_bf16 v[28:31], v[186:189], v[226:229], v[28:31]
	v_mfma_f32_16x16x32_bf16 v[20:23], v[140:143], v[236:239], v[20:23]
	v_mfma_f32_16x16x32_bf16 v[12:15], v[186:189], v[236:239], v[12:15]
	s_setprio 0
	s_setprio 1
	v_mfma_f32_16x16x32_bf16 v[48:51], v[190:193], v[206:209], v[48:51]
	v_mfma_f32_16x16x32_bf16 v[40:43], v[198:201], v[206:209], v[40:43]
	v_mfma_f32_16x16x32_bf16 v[32:35], v[190:193], v[214:217], v[32:35]
	v_mfma_f32_16x16x32_bf16 v[24:27], v[198:201], v[214:217], v[24:27]
	v_mfma_f32_16x16x32_bf16 v[16:19], v[190:193], v[222:225], v[16:19]
	v_mfma_f32_16x16x32_bf16 v[8:11], v[198:201], v[222:225], v[8:11]
	v_mfma_f32_16x16x32_bf16 v[4:7], v[190:193], v[230:233], v[4:7]
	v_mfma_f32_16x16x32_bf16 v[0:3], v[198:201], v[230:233], v[0:3]
	v_mfma_f32_16x16x32_bf16 v[48:51], v[194:197], v[210:213], v[48:51]
	v_mfma_f32_16x16x32_bf16 v[40:43], v[202:205], v[210:213], v[40:43]
	v_mfma_f32_16x16x32_bf16 v[32:35], v[194:197], v[218:221], v[32:35]
	v_mfma_f32_16x16x32_bf16 v[24:27], v[202:205], v[218:221], v[24:27]
	v_mfma_f32_16x16x32_bf16 v[16:19], v[194:197], v[226:229], v[16:19]
	v_mfma_f32_16x16x32_bf16 v[8:11], v[202:205], v[226:229], v[8:11]
	v_mfma_f32_16x16x32_bf16 v[4:7], v[194:197], v[236:239], v[4:7]
	v_mfma_f32_16x16x32_bf16 v[0:3], v[202:205], v[236:239], v[0:3]
	s_setprio 0
	s_barrier
	s_add_i32 s25, 0, 0x18000
	v_add_u32_e32 v168, s25, v173
	s_add_i32 s27, 0, 0x1c000
	ds_read_b128 v[136:139], v168
	ds_read_b128 v[140:143], v168 offset:1024
	ds_read_b128 v[178:181], v168 offset:2048
	ds_read_b128 v[186:189], v168 offset:3072
	v_add_u32_e32 v168, s27, v173
	ds_read_b128 v[190:193], v168
	ds_read_b128 v[194:197], v168 offset:1024
	ds_read_b128 v[198:201], v168 offset:2048
	ds_read_b128 v[202:205], v168 offset:3072
	v_lshl_add_u64 v[170:171], v[170:171], 0, s[6:7]
	s_mov_b32 m0, s35
	v_lshl_add_u64 v[248:249], v[170:171], 0, v[150:151]
	ds_read_b128 v[206:209], v176 offset:32768
	ds_read_b128 v[210:213], v176 offset:33792
	ds_read_b128 v[214:217], v176 offset:34816
	ds_read_b128 v[218:221], v176 offset:35840
	ds_read_b128 v[222:225], v176 offset:36864
	ds_read_b128 v[226:229], v176 offset:37888
	ds_read_b128 v[230:233], v176 offset:38912
	ds_read_b128 v[236:239], v176 offset:39936
	s_mov_b32 m0, s29
	s_nop 0
	global_load_lds_dwordx4 v[244:245], off
	s_mov_b32 m0, s31
	s_nop 0
	global_load_lds_dwordx4 v[246:247], off
	s_mov_b32 m0, s35
	s_nop 0
	global_load_lds_dwordx4 v[248:249], off
	v_lshl_add_u64 v[170:171], v[170:171], 0, v[146:147]
	s_mov_b32 m0, s40
	s_nop 0
	global_load_lds_dwordx4 v[170:171], off
	s_waitcnt vmcnt(8)
	s_waitcnt lgkmcnt(0)
	s_barrier
	s_setprio 1
	s_waitcnt lgkmcnt(0)
	v_mfma_f32_16x16x32_bf16 v[124:127], v[136:139], v[206:209], v[124:127]
	v_mfma_f32_16x16x32_bf16 v[120:123], v[178:181], v[206:209], v[120:123]
	v_mfma_f32_16x16x32_bf16 v[116:119], v[136:139], v[214:217], v[116:119]
	v_mfma_f32_16x16x32_bf16 v[112:115], v[178:181], v[214:217], v[112:115]
	v_mfma_f32_16x16x32_bf16 v[108:111], v[136:139], v[222:225], v[108:111]
	v_mfma_f32_16x16x32_bf16 v[96:99], v[178:181], v[222:225], v[96:99]
	v_mfma_f32_16x16x32_bf16 v[84:87], v[136:139], v[230:233], v[84:87]
	v_mfma_f32_16x16x32_bf16 v[76:79], v[178:181], v[230:233], v[76:79]
	v_mfma_f32_16x16x32_bf16 v[124:127], v[140:143], v[210:213], v[124:127]
	v_mfma_f32_16x16x32_bf16 v[120:123], v[186:189], v[210:213], v[120:123]
	v_mfma_f32_16x16x32_bf16 v[116:119], v[140:143], v[218:221], v[116:119]
	v_mfma_f32_16x16x32_bf16 v[112:115], v[186:189], v[218:221], v[112:115]
	v_mfma_f32_16x16x32_bf16 v[108:111], v[140:143], v[226:229], v[108:111]
	v_mfma_f32_16x16x32_bf16 v[96:99], v[186:189], v[226:229], v[96:99]
	v_mfma_f32_16x16x32_bf16 v[84:87], v[140:143], v[236:239], v[84:87]
	v_mfma_f32_16x16x32_bf16 v[76:79], v[186:189], v[236:239], v[76:79]
	s_setprio 0
	s_setprio 1
	v_mfma_f32_16x16x32_bf16 v[104:107], v[190:193], v[206:209], v[104:107]
	v_mfma_f32_16x16x32_bf16 v[100:103], v[198:201], v[206:209], v[100:103]
	v_mfma_f32_16x16x32_bf16 v[92:95], v[190:193], v[214:217], v[92:95]
	v_mfma_f32_16x16x32_bf16 v[88:91], v[198:201], v[214:217], v[88:91]
	v_mfma_f32_16x16x32_bf16 v[80:83], v[190:193], v[222:225], v[80:83]
	v_mfma_f32_16x16x32_bf16 v[72:75], v[198:201], v[222:225], v[72:75]
	v_mfma_f32_16x16x32_bf16 v[68:71], v[190:193], v[230:233], v[68:71]
	v_mfma_f32_16x16x32_bf16 v[64:67], v[198:201], v[230:233], v[64:67]
	v_mfma_f32_16x16x32_bf16 v[104:107], v[194:197], v[210:213], v[104:107]
	v_mfma_f32_16x16x32_bf16 v[100:103], v[202:205], v[210:213], v[100:103]
	v_mfma_f32_16x16x32_bf16 v[92:95], v[194:197], v[218:221], v[92:95]
	v_mfma_f32_16x16x32_bf16 v[88:91], v[202:205], v[218:221], v[88:91]
	v_mfma_f32_16x16x32_bf16 v[80:83], v[194:197], v[226:229], v[80:83]
	v_mfma_f32_16x16x32_bf16 v[72:75], v[202:205], v[226:229], v[72:75]
	v_mfma_f32_16x16x32_bf16 v[68:71], v[194:197], v[236:239], v[68:71]
	v_mfma_f32_16x16x32_bf16 v[64:67], v[202:205], v[236:239], v[64:67]
	s_setprio 0
	s_barrier
	s_add_i32 s25, s25, s33
	v_lshl_add_u64 v[170:171], v[240:241], 0, s[12:13]
	s_mov_b32 m0, s25
	ds_read_b128 v[206:209], v176 offset:49152
	ds_read_b128 v[210:213], v176 offset:50176
	ds_read_b128 v[214:217], v176 offset:51200
	ds_read_b128 v[218:221], v176 offset:52224
	ds_read_b128 v[222:225], v176 offset:53248
	ds_read_b128 v[226:229], v176 offset:54272
	ds_read_b128 v[230:233], v176 offset:55296
	ds_read_b128 v[236:239], v176 offset:56320
	global_load_lds_dwordx4 v[170:171], off
	v_lshl_add_u64 v[170:171], v[242:243], 0, s[12:13]
	s_add_i32 m0, s25, 0x2000
	s_add_i32 s25, s27, s33
	global_load_lds_dwordx4 v[170:171], off
	v_lshl_add_u64 v[170:171], v[182:183], 0, s[14:15]
	v_lshl_add_u64 v[182:183], v[170:171], 0, v[148:149]
	s_mov_b32 m0, s25
	v_lshl_add_u64 v[170:171], v[170:171], 0, v[144:145]
	global_load_lds_dwordx4 v[182:183], off
	s_add_i32 m0, s25, 0x2000
	s_nop 0
	global_load_lds_dwordx4 v[170:171], off
	v_lshl_add_u64 v[170:171], v[244:245], 0, s[12:13]
	s_mov_b32 m0, s42
	s_nop 0
	global_load_lds_dwordx4 v[170:171], off
	v_lshl_add_u64 v[170:171], v[246:247], 0, s[12:13]
	s_mov_b32 m0, s43
	s_nop 0
	global_load_lds_dwordx4 v[170:171], off
	s_waitcnt vmcnt(8)
	s_waitcnt lgkmcnt(0)
	s_barrier
	s_setprio 1
	s_waitcnt lgkmcnt(0)
	v_mfma_f32_16x16x32_bf16 v[60:63], v[136:139], v[206:209], v[60:63]
	v_mfma_f32_16x16x32_bf16 v[56:59], v[178:181], v[206:209], v[56:59]
	v_mfma_f32_16x16x32_bf16 v[52:55], v[136:139], v[214:217], v[52:55]
	v_mfma_f32_16x16x32_bf16 v[44:47], v[178:181], v[214:217], v[44:47]
	v_mfma_f32_16x16x32_bf16 v[36:39], v[136:139], v[222:225], v[36:39]
	v_mfma_f32_16x16x32_bf16 v[28:31], v[178:181], v[222:225], v[28:31]
	v_mfma_f32_16x16x32_bf16 v[20:23], v[136:139], v[230:233], v[20:23]
	v_mfma_f32_16x16x32_bf16 v[12:15], v[178:181], v[230:233], v[12:15]
	v_mfma_f32_16x16x32_bf16 v[60:63], v[140:143], v[210:213], v[60:63]
	v_mfma_f32_16x16x32_bf16 v[56:59], v[186:189], v[210:213], v[56:59]
	v_mfma_f32_16x16x32_bf16 v[52:55], v[140:143], v[218:221], v[52:55]
	v_mfma_f32_16x16x32_bf16 v[44:47], v[186:189], v[218:221], v[44:47]
	v_mfma_f32_16x16x32_bf16 v[36:39], v[140:143], v[226:229], v[36:39]
	v_mfma_f32_16x16x32_bf16 v[28:31], v[186:189], v[226:229], v[28:31]
	v_mfma_f32_16x16x32_bf16 v[20:23], v[140:143], v[236:239], v[20:23]
	v_mfma_f32_16x16x32_bf16 v[12:15], v[186:189], v[236:239], v[12:15]
	s_setprio 0
	s_setprio 1
	v_mfma_f32_16x16x32_bf16 v[48:51], v[190:193], v[206:209], v[48:51]
	v_mfma_f32_16x16x32_bf16 v[40:43], v[198:201], v[206:209], v[40:43]
	v_mfma_f32_16x16x32_bf16 v[32:35], v[190:193], v[214:217], v[32:35]
	v_mfma_f32_16x16x32_bf16 v[24:27], v[198:201], v[214:217], v[24:27]
	v_mfma_f32_16x16x32_bf16 v[16:19], v[190:193], v[222:225], v[16:19]
	v_mfma_f32_16x16x32_bf16 v[8:11], v[198:201], v[222:225], v[8:11]
	v_mfma_f32_16x16x32_bf16 v[4:7], v[190:193], v[230:233], v[4:7]
	v_mfma_f32_16x16x32_bf16 v[0:3], v[198:201], v[230:233], v[0:3]
	v_mfma_f32_16x16x32_bf16 v[48:51], v[194:197], v[210:213], v[48:51]
	v_mfma_f32_16x16x32_bf16 v[40:43], v[202:205], v[210:213], v[40:43]
	v_mfma_f32_16x16x32_bf16 v[32:35], v[194:197], v[218:221], v[32:35]
	v_mfma_f32_16x16x32_bf16 v[24:27], v[202:205], v[218:221], v[24:27]
	v_mfma_f32_16x16x32_bf16 v[16:19], v[194:197], v[226:229], v[16:19]
	v_mfma_f32_16x16x32_bf16 v[8:11], v[202:205], v[226:229], v[8:11]
	v_mfma_f32_16x16x32_bf16 v[4:7], v[194:197], v[236:239], v[4:7]
	v_mfma_f32_16x16x32_bf16 v[0:3], v[202:205], v[236:239], v[0:3]
	s_setprio 0
	s_barrier
	s_add_i32 s23, s23, 2
	v_lshl_add_u64 v[132:133], v[132:133], 0, s[18:19]
	s_cmp_gt_u32 s23, 13
	v_lshl_add_u64 v[134:135], v[134:135], 0, s[18:19]
	s_cbranch_scc0 .LBB0_241
	s_and_b64 vcc, exec, s[16:17]
	s_cbranch_vccz .LBB0_244
	s_barrier

.LBB0_441:
	ds_read_b128 v[168:171], v165
	ds_read_b128 v[172:175], v165 offset:1024
	ds_read_b128 v[176:179], v165 offset:2048
	ds_read_b128 v[180:183], v165 offset:3072
	ds_read_b128 v[186:189], v166
	ds_read_b128 v[190:193], v166 offset:1024
	ds_read_b128 v[194:197], v166 offset:2048
	ds_read_b128 v[198:201], v166 offset:3072
	s_cmp_eq_u32 s29, 12
	v_lshl_add_u64 v[202:203], v[154:155], 0, s[26:27]
	s_cselect_b64 vcc, -1, 0
	v_cndmask_b32_e32 v237, v203, v151, vcc
	v_cndmask_b32_e32 v236, v202, v150, vcc
	v_cndmask_b32_e32 v239, v157, v153, vcc
	v_cndmask_b32_e32 v238, v156, v152, vcc
	v_lshl_add_u64 v[240:241], v[154:155], 0, v[138:139]
	s_add_i32 m0, s33, 0xc000
	ds_read_b128 v[202:205], v167
	ds_read_b128 v[206:209], v167 offset:1024
	ds_read_b128 v[210:213], v167 offset:2048
	ds_read_b128 v[214:217], v167 offset:3072
	ds_read_b128 v[218:221], v167 offset:4096
	ds_read_b128 v[222:225], v167 offset:5120
	ds_read_b128 v[226:229], v167 offset:6144
	ds_read_b128 v[230:233], v167 offset:7168
	global_load_lds_dwordx4 v[240:241], off
	v_lshl_add_u64 v[240:241], v[154:155], 0, v[140:141]
	s_add_i32 m0, s33, 0xe000
	s_nop 0
	global_load_lds_dwordx4 v[240:241], off
	s_waitcnt vmcnt(8)
	s_waitcnt lgkmcnt(0)
	s_barrier
	s_setprio 1
	s_waitcnt lgkmcnt(0)
	v_mfma_f32_16x16x32_bf16 v[124:127], v[168:171], v[202:205], v[124:127]
	v_mfma_f32_16x16x32_bf16 v[120:123], v[176:179], v[202:205], v[120:123]
	v_mfma_f32_16x16x32_bf16 v[108:111], v[168:171], v[210:213], v[108:111]
	v_mfma_f32_16x16x32_bf16 v[104:107], v[176:179], v[210:213], v[104:107]
	v_mfma_f32_16x16x32_bf16 v[92:95], v[168:171], v[218:221], v[92:95]
	v_mfma_f32_16x16x32_bf16 v[88:91], v[176:179], v[218:221], v[88:91]
	v_mfma_f32_16x16x32_bf16 v[76:79], v[168:171], v[226:229], v[76:79]
	v_mfma_f32_16x16x32_bf16 v[72:75], v[176:179], v[226:229], v[72:75]
	v_mfma_f32_16x16x32_bf16 v[124:127], v[172:175], v[206:209], v[124:127]
	v_mfma_f32_16x16x32_bf16 v[120:123], v[180:183], v[206:209], v[120:123]
	v_mfma_f32_16x16x32_bf16 v[108:111], v[172:175], v[214:217], v[108:111]
	v_mfma_f32_16x16x32_bf16 v[104:107], v[180:183], v[214:217], v[104:107]
	v_mfma_f32_16x16x32_bf16 v[92:95], v[172:175], v[222:225], v[92:95]
	v_mfma_f32_16x16x32_bf16 v[88:91], v[180:183], v[222:225], v[88:91]
	v_mfma_f32_16x16x32_bf16 v[76:79], v[172:175], v[230:233], v[76:79]
	v_mfma_f32_16x16x32_bf16 v[72:75], v[180:183], v[230:233], v[72:75]
	s_setprio 0
	s_setprio 1
	v_mfma_f32_16x16x32_bf16 v[116:119], v[186:189], v[202:205], v[116:119]
	v_mfma_f32_16x16x32_bf16 v[112:115], v[194:197], v[202:205], v[112:115]
	v_mfma_f32_16x16x32_bf16 v[100:103], v[186:189], v[210:213], v[100:103]
	v_mfma_f32_16x16x32_bf16 v[96:99], v[194:197], v[210:213], v[96:99]
	v_mfma_f32_16x16x32_bf16 v[84:87], v[186:189], v[218:221], v[84:87]
	v_mfma_f32_16x16x32_bf16 v[80:83], v[194:197], v[218:221], v[80:83]
	v_mfma_f32_16x16x32_bf16 v[68:71], v[186:189], v[226:229], v[68:71]
	v_mfma_f32_16x16x32_bf16 v[64:67], v[194:197], v[226:229], v[64:67]
	v_mfma_f32_16x16x32_bf16 v[116:119], v[190:193], v[206:209], v[116:119]
	v_mfma_f32_16x16x32_bf16 v[112:115], v[198:201], v[206:209], v[112:115]
	v_mfma_f32_16x16x32_bf16 v[100:103], v[190:193], v[214:217], v[100:103]
	v_mfma_f32_16x16x32_bf16 v[96:99], v[198:201], v[214:217], v[96:99]
	v_mfma_f32_16x16x32_bf16 v[84:87], v[190:193], v[222:225], v[84:87]
	v_mfma_f32_16x16x32_bf16 v[80:83], v[198:201], v[222:225], v[80:83]
	v_mfma_f32_16x16x32_bf16 v[68:71], v[190:193], v[230:233], v[68:71]
	v_mfma_f32_16x16x32_bf16 v[64:67], v[198:201], v[230:233], v[64:67]
	s_setprio 0
	s_barrier
	s_add_i32 s31, s51, s22
	v_lshl_add_u64 v[240:241], v[238:239], 0, v[134:135]
	s_mov_b32 m0, s31
	ds_read_b128 v[202:205], v167 offset:16384
	ds_read_b128 v[206:209], v167 offset:17408
	ds_read_b128 v[210:213], v167 offset:18432
	ds_read_b128 v[214:217], v167 offset:19456
	ds_read_b128 v[218:221], v167 offset:20480
	ds_read_b128 v[222:225], v167 offset:21504
	ds_read_b128 v[226:229], v167 offset:22528
	ds_read_b128 v[230:233], v167 offset:23552
	global_load_lds_dwordx4 v[240:241], off
	v_lshl_add_u64 v[242:243], v[238:239], 0, v[130:131]
	s_add_i32 m0, s31, 0x2000
	v_lshl_add_u64 v[244:245], v[238:239], 0, s[10:11]
	s_add_i32 s31, s52, s22
	global_load_lds_dwordx4 v[242:243], off
	v_lshl_add_u64 v[246:247], v[244:245], 0, v[134:135]
	s_mov_b32 m0, s31
	v_lshl_add_u64 v[244:245], v[244:245], 0, v[130:131]
	global_load_lds_dwordx4 v[246:247], off
	s_add_i32 m0, s31, 0x2000
	v_lshl_add_u64 v[246:247], v[236:237], 0, v[132:133]
	global_load_lds_dwordx4 v[244:245], off
	v_lshl_add_u64 v[244:245], v[236:237], 0, v[136:137]
	s_waitcnt vmcnt(6)
	s_waitcnt lgkmcnt(0)
	s_barrier
	s_setprio 1
	s_waitcnt lgkmcnt(0)
	v_mfma_f32_16x16x32_bf16 v[60:63], v[168:171], v[202:205], v[60:63]
	v_mfma_f32_16x16x32_bf16 v[56:59], v[176:179], v[202:205], v[56:59]
	v_mfma_f32_16x16x32_bf16 v[44:47], v[168:171], v[210:213], v[44:47]
	v_mfma_f32_16x16x32_bf16 v[40:43], v[176:179], v[210:213], v[40:43]
	v_mfma_f32_16x16x32_bf16 v[28:31], v[168:171], v[218:221], v[28:31]
	v_mfma_f32_16x16x32_bf16 v[24:27], v[176:179], v[218:221], v[24:27]
	v_mfma_f32_16x16x32_bf16 v[12:15], v[168:171], v[226:229], v[12:15]
	v_mfma_f32_16x16x32_bf16 v[8:11], v[176:179], v[226:229], v[8:11]
	v_mfma_f32_16x16x32_bf16 v[60:63], v[172:175], v[206:209], v[60:63]
	v_mfma_f32_16x16x32_bf16 v[56:59], v[180:183], v[206:209], v[56:59]
	v_mfma_f32_16x16x32_bf16 v[44:47], v[172:175], v[214:217], v[44:47]
	v_mfma_f32_16x16x32_bf16 v[40:43], v[180:183], v[214:217], v[40:43]
	v_mfma_f32_16x16x32_bf16 v[28:31], v[172:175], v[222:225], v[28:31]
	v_mfma_f32_16x16x32_bf16 v[24:27], v[180:183], v[222:225], v[24:27]
	v_mfma_f32_16x16x32_bf16 v[12:15], v[172:175], v[230:233], v[12:15]
	v_mfma_f32_16x16x32_bf16 v[8:11], v[180:183], v[230:233], v[8:11]
	s_setprio 0
	s_setprio 1
	v_mfma_f32_16x16x32_bf16 v[52:55], v[186:189], v[202:205], v[52:55]
	v_mfma_f32_16x16x32_bf16 v[48:51], v[194:197], v[202:205], v[48:51]
	v_mfma_f32_16x16x32_bf16 v[36:39], v[186:189], v[210:213], v[36:39]
	v_mfma_f32_16x16x32_bf16 v[32:35], v[194:197], v[210:213], v[32:35]
	v_mfma_f32_16x16x32_bf16 v[20:23], v[186:189], v[218:221], v[20:23]
	v_mfma_f32_16x16x32_bf16 v[16:19], v[194:197], v[218:221], v[16:19]
	v_mfma_f32_16x16x32_bf16 v[4:7], v[186:189], v[226:229], v[4:7]
	v_mfma_f32_16x16x32_bf16 v[0:3], v[194:197], v[226:229], v[0:3]
	v_mfma_f32_16x16x32_bf16 v[52:55], v[190:193], v[206:209], v[52:55]
	v_mfma_f32_16x16x32_bf16 v[48:51], v[198:201], v[206:209], v[48:51]
	v_mfma_f32_16x16x32_bf16 v[36:39], v[190:193], v[214:217], v[36:39]
	v_mfma_f32_16x16x32_bf16 v[32:35], v[198:201], v[214:217], v[32:35]
	v_mfma_f32_16x16x32_bf16 v[20:23], v[190:193], v[222:225], v[20:23]
	v_mfma_f32_16x16x32_bf16 v[16:19], v[198:201], v[222:225], v[16:19]
	v_mfma_f32_16x16x32_bf16 v[4:7], v[190:193], v[230:233], v[4:7]
	v_mfma_f32_16x16x32_bf16 v[0:3], v[198:201], v[230:233], v[0:3]
	s_setprio 0
	s_barrier
	s_add_i32 s31, 0, 0x18000
	s_add_i32 s35, 0, 0x1c000
	v_add_u32_e32 v180, s31, v164
	v_add_u32_e32 v198, s35, v164
	ds_read_b128 v[168:171], v180
	ds_read_b128 v[172:175], v180 offset:1024
	ds_read_b128 v[176:179], v180 offset:2048
	ds_read_b128 v[180:183], v180 offset:3072
	ds_read_b128 v[186:189], v198
	ds_read_b128 v[190:193], v198 offset:1024
	ds_read_b128 v[194:197], v198 offset:2048
	ds_read_b128 v[198:201], v198 offset:3072
	v_lshl_add_u64 v[236:237], v[236:237], 0, s[10:11]
	s_mov_b32 m0, s39
	v_lshl_add_u64 v[248:249], v[236:237], 0, v[136:137]
	ds_read_b128 v[202:205], v167 offset:32768
	ds_read_b128 v[206:209], v167 offset:33792
	ds_read_b128 v[210:213], v167 offset:34816
	ds_read_b128 v[214:217], v167 offset:35840
	ds_read_b128 v[218:221], v167 offset:36864
	ds_read_b128 v[222:225], v167 offset:37888
	ds_read_b128 v[226:229], v167 offset:38912
	ds_read_b128 v[230:233], v167 offset:39936
	s_mov_b32 m0, s33
	s_nop 0
	global_load_lds_dwordx4 v[244:245], off
	s_mov_b32 m0, s37
	s_nop 0
	global_load_lds_dwordx4 v[246:247], off
	s_mov_b32 m0, s39
	s_nop 0
	global_load_lds_dwordx4 v[248:249], off
	v_lshl_add_u64 v[236:237], v[236:237], 0, v[132:133]
	s_mov_b32 m0, s42
	s_nop 0
	global_load_lds_dwordx4 v[236:237], off
	s_waitcnt vmcnt(8)
	s_waitcnt lgkmcnt(0)
	s_barrier
	s_setprio 1
	s_waitcnt lgkmcnt(0)
	v_mfma_f32_16x16x32_bf16 v[124:127], v[168:171], v[202:205], v[124:127]
	v_mfma_f32_16x16x32_bf16 v[120:123], v[176:179], v[202:205], v[120:123]
	v_mfma_f32_16x16x32_bf16 v[108:111], v[168:171], v[210:213], v[108:111]
	v_mfma_f32_16x16x32_bf16 v[104:107], v[176:179], v[210:213], v[104:107]
	v_mfma_f32_16x16x32_bf16 v[92:95], v[168:171], v[218:221], v[92:95]
	v_mfma_f32_16x16x32_bf16 v[88:91], v[176:179], v[218:221], v[88:91]
	v_mfma_f32_16x16x32_bf16 v[76:79], v[168:171], v[226:229], v[76:79]
	v_mfma_f32_16x16x32_bf16 v[72:75], v[176:179], v[226:229], v[72:75]
	v_mfma_f32_16x16x32_bf16 v[124:127], v[172:175], v[206:209], v[124:127]
	v_mfma_f32_16x16x32_bf16 v[120:123], v[180:183], v[206:209], v[120:123]
	v_mfma_f32_16x16x32_bf16 v[108:111], v[172:175], v[214:217], v[108:111]
	v_mfma_f32_16x16x32_bf16 v[104:107], v[180:183], v[214:217], v[104:107]
	v_mfma_f32_16x16x32_bf16 v[92:95], v[172:175], v[222:225], v[92:95]
	v_mfma_f32_16x16x32_bf16 v[88:91], v[180:183], v[222:225], v[88:91]
	v_mfma_f32_16x16x32_bf16 v[76:79], v[172:175], v[230:233], v[76:79]
	v_mfma_f32_16x16x32_bf16 v[72:75], v[180:183], v[230:233], v[72:75]
	s_setprio 0
	s_setprio 1
	v_mfma_f32_16x16x32_bf16 v[116:119], v[186:189], v[202:205], v[116:119]
	v_mfma_f32_16x16x32_bf16 v[112:115], v[194:197], v[202:205], v[112:115]
	v_mfma_f32_16x16x32_bf16 v[100:103], v[186:189], v[210:213], v[100:103]
	v_mfma_f32_16x16x32_bf16 v[96:99], v[194:197], v[210:213], v[96:99]
	v_mfma_f32_16x16x32_bf16 v[84:87], v[186:189], v[218:221], v[84:87]
	v_mfma_f32_16x16x32_bf16 v[80:83], v[194:197], v[218:221], v[80:83]
	v_mfma_f32_16x16x32_bf16 v[68:71], v[186:189], v[226:229], v[68:71]
	v_mfma_f32_16x16x32_bf16 v[64:67], v[194:197], v[226:229], v[64:67]
	v_mfma_f32_16x16x32_bf16 v[116:119], v[190:193], v[206:209], v[116:119]
	v_mfma_f32_16x16x32_bf16 v[112:115], v[198:201], v[206:209], v[112:115]
	v_mfma_f32_16x16x32_bf16 v[100:103], v[190:193], v[214:217], v[100:103]
	v_mfma_f32_16x16x32_bf16 v[96:99], v[198:201], v[214:217], v[96:99]
	v_mfma_f32_16x16x32_bf16 v[84:87], v[190:193], v[222:225], v[84:87]
	v_mfma_f32_16x16x32_bf16 v[80:83], v[198:201], v[222:225], v[80:83]
	v_mfma_f32_16x16x32_bf16 v[68:71], v[190:193], v[230:233], v[68:71]
	v_mfma_f32_16x16x32_bf16 v[64:67], v[198:201], v[230:233], v[64:67]
	s_setprio 0
	s_barrier
	s_add_i32 s31, s31, s22
	v_lshl_add_u64 v[236:237], v[240:241], 0, s[16:17]
	s_mov_b32 m0, s31
	ds_read_b128 v[202:205], v167 offset:49152
	ds_read_b128 v[206:209], v167 offset:50176
	ds_read_b128 v[210:213], v167 offset:51200
	ds_read_b128 v[214:217], v167 offset:52224
	ds_read_b128 v[218:221], v167 offset:53248
	ds_read_b128 v[222:225], v167 offset:54272
	ds_read_b128 v[226:229], v167 offset:55296
	ds_read_b128 v[230:233], v167 offset:56320
	global_load_lds_dwordx4 v[236:237], off
	v_lshl_add_u64 v[236:237], v[242:243], 0, s[16:17]
	s_add_i32 m0, s31, 0x2000
	s_add_i32 s31, s35, s22
	global_load_lds_dwordx4 v[236:237], off
	v_lshl_add_u64 v[236:237], v[238:239], 0, s[18:19]
	v_lshl_add_u64 v[238:239], v[236:237], 0, v[134:135]
	s_mov_b32 m0, s31
	v_lshl_add_u64 v[236:237], v[236:237], 0, v[130:131]
	global_load_lds_dwordx4 v[238:239], off
	s_add_i32 m0, s31, 0x2000
	s_nop 0
	global_load_lds_dwordx4 v[236:237], off
	v_lshl_add_u64 v[236:237], v[244:245], 0, s[16:17]
	s_mov_b32 m0, s44
	s_nop 0
	global_load_lds_dwordx4 v[236:237], off
	v_lshl_add_u64 v[236:237], v[246:247], 0, s[16:17]
	s_mov_b32 m0, s45
	s_nop 0
	global_load_lds_dwordx4 v[236:237], off
	s_waitcnt vmcnt(8)
	s_waitcnt lgkmcnt(0)
	s_barrier
	s_setprio 1
	s_waitcnt lgkmcnt(0)
	v_mfma_f32_16x16x32_bf16 v[60:63], v[168:171], v[202:205], v[60:63]
	v_mfma_f32_16x16x32_bf16 v[56:59], v[176:179], v[202:205], v[56:59]
	v_mfma_f32_16x16x32_bf16 v[44:47], v[168:171], v[210:213], v[44:47]
	v_mfma_f32_16x16x32_bf16 v[40:43], v[176:179], v[210:213], v[40:43]
	v_mfma_f32_16x16x32_bf16 v[28:31], v[168:171], v[218:221], v[28:31]
	v_mfma_f32_16x16x32_bf16 v[24:27], v[176:179], v[218:221], v[24:27]
	v_mfma_f32_16x16x32_bf16 v[12:15], v[168:171], v[226:229], v[12:15]
	v_mfma_f32_16x16x32_bf16 v[8:11], v[176:179], v[226:229], v[8:11]
	v_mfma_f32_16x16x32_bf16 v[60:63], v[172:175], v[206:209], v[60:63]
	v_mfma_f32_16x16x32_bf16 v[56:59], v[180:183], v[206:209], v[56:59]
	v_mfma_f32_16x16x32_bf16 v[44:47], v[172:175], v[214:217], v[44:47]
	v_mfma_f32_16x16x32_bf16 v[40:43], v[180:183], v[214:217], v[40:43]
	v_mfma_f32_16x16x32_bf16 v[28:31], v[172:175], v[222:225], v[28:31]
	v_mfma_f32_16x16x32_bf16 v[24:27], v[180:183], v[222:225], v[24:27]
	v_mfma_f32_16x16x32_bf16 v[12:15], v[172:175], v[230:233], v[12:15]
	v_mfma_f32_16x16x32_bf16 v[8:11], v[180:183], v[230:233], v[8:11]
	s_setprio 0
	s_setprio 1
	v_mfma_f32_16x16x32_bf16 v[52:55], v[186:189], v[202:205], v[52:55]
	v_mfma_f32_16x16x32_bf16 v[48:51], v[194:197], v[202:205], v[48:51]
	v_mfma_f32_16x16x32_bf16 v[36:39], v[186:189], v[210:213], v[36:39]
	v_mfma_f32_16x16x32_bf16 v[32:35], v[194:197], v[210:213], v[32:35]
	v_mfma_f32_16x16x32_bf16 v[20:23], v[186:189], v[218:221], v[20:23]
	v_mfma_f32_16x16x32_bf16 v[16:19], v[194:197], v[218:221], v[16:19]
	v_mfma_f32_16x16x32_bf16 v[4:7], v[186:189], v[226:229], v[4:7]
	v_mfma_f32_16x16x32_bf16 v[0:3], v[194:197], v[226:229], v[0:3]
	v_mfma_f32_16x16x32_bf16 v[52:55], v[190:193], v[206:209], v[52:55]
	v_mfma_f32_16x16x32_bf16 v[48:51], v[198:201], v[206:209], v[48:51]
	v_mfma_f32_16x16x32_bf16 v[36:39], v[190:193], v[214:217], v[36:39]
	v_mfma_f32_16x16x32_bf16 v[32:35], v[198:201], v[214:217], v[32:35]
	v_mfma_f32_16x16x32_bf16 v[20:23], v[190:193], v[222:225], v[20:23]
	v_mfma_f32_16x16x32_bf16 v[16:19], v[198:201], v[222:225], v[16:19]
	v_mfma_f32_16x16x32_bf16 v[4:7], v[190:193], v[230:233], v[4:7]
	v_mfma_f32_16x16x32_bf16 v[0:3], v[198:201], v[230:233], v[0:3]
	s_setprio 0
	s_barrier
	s_add_i32 s29, s29, 2
	v_lshl_add_u64 v[154:155], v[154:155], 0, s[24:25]
	s_cmp_gt_u32 s29, 13
	v_lshl_add_u64 v[156:157], v[156:157], 0, s[24:25]
	s_cbranch_scc0 .LBB0_441
	s_and_b64 vcc, exec, s[20:21]
	s_cbranch_vccz .LBB0_444
	s_barrier

.LBB0_698:
	s_waitcnt vmcnt(0)
	ds_read_b128 v[64:67], v203
	ds_read_b128 v[68:71], v203 offset:1024
	ds_read_b128 v[72:75], v203 offset:2048
	ds_read_b128 v[84:87], v203 offset:3072
	ds_read_b128 v[88:91], v204
	ds_read_b128 v[100:103], v204 offset:1024
	ds_read_b128 v[188:191], v204 offset:2048
	ds_read_b128 v[192:195], v204 offset:3072
	s_cmp_eq_u32 s9, 12
	v_lshl_add_u64 v[196:197], v[52:53], 0, s[24:25]
	s_cselect_b64 vcc, -1, 0
	v_cndmask_b32_e32 v237, v197, v49, vcc
	v_cndmask_b32_e32 v236, v196, v48, vcc
	v_cndmask_b32_e32 v239, v55, v51, vcc
	v_cndmask_b32_e32 v238, v54, v50, vcc
	s_mov_b32 m0, s64
	v_lshl_add_u64 v[240:241], v[52:53], 0, v[174:175]
	ds_read_b128 v[196:199], v205
	ds_read_b128 v[206:209], v205 offset:1024
	ds_read_b128 v[210:213], v205 offset:2048
	ds_read_b128 v[214:217], v205 offset:3072
	ds_read_b128 v[218:221], v205 offset:4096
	ds_read_b128 v[222:225], v205 offset:5120
	ds_read_b128 v[226:229], v205 offset:6144
	ds_read_b128 v[230:233], v205 offset:7168
	global_load_lds_dwordx4 v[240:241], off
	v_lshl_add_u64 v[240:241], v[52:53], 0, v[176:177]
	s_mov_b32 m0, s65
	s_nop 0
	global_load_lds_dwordx4 v[240:241], off
	s_waitcnt vmcnt(8)
	s_waitcnt lgkmcnt(0)
	s_barrier
	s_setprio 1
	s_waitcnt lgkmcnt(0)
	v_mfma_f32_16x16x32_bf16 v[156:159], v[64:67], v[196:199], v[156:159]
	v_mfma_f32_16x16x32_bf16 v[152:155], v[72:75], v[196:199], v[152:155]
	v_mfma_f32_16x16x32_bf16 v[140:143], v[64:67], v[210:213], v[140:143]
	v_mfma_f32_16x16x32_bf16 v[136:139], v[72:75], v[210:213], v[136:139]
	v_mfma_f32_16x16x32_bf16 v[124:127], v[64:67], v[218:221], v[124:127]
	v_mfma_f32_16x16x32_bf16 v[120:123], v[72:75], v[218:221], v[120:123]
	v_mfma_f32_16x16x32_bf16 v[108:111], v[64:67], v[226:229], v[108:111]
	v_mfma_f32_16x16x32_bf16 v[104:107], v[72:75], v[226:229], v[104:107]
	v_mfma_f32_16x16x32_bf16 v[156:159], v[68:71], v[206:209], v[156:159]
	v_mfma_f32_16x16x32_bf16 v[152:155], v[84:87], v[206:209], v[152:155]
	v_mfma_f32_16x16x32_bf16 v[140:143], v[68:71], v[214:217], v[140:143]
	v_mfma_f32_16x16x32_bf16 v[136:139], v[84:87], v[214:217], v[136:139]
	v_mfma_f32_16x16x32_bf16 v[124:127], v[68:71], v[222:225], v[124:127]
	v_mfma_f32_16x16x32_bf16 v[120:123], v[84:87], v[222:225], v[120:123]
	v_mfma_f32_16x16x32_bf16 v[108:111], v[68:71], v[230:233], v[108:111]
	v_mfma_f32_16x16x32_bf16 v[104:107], v[84:87], v[230:233], v[104:107]
	s_setprio 0
	s_setprio 1
	v_mfma_f32_16x16x32_bf16 v[148:151], v[88:91], v[196:199], v[148:151]
	v_mfma_f32_16x16x32_bf16 v[144:147], v[188:191], v[196:199], v[144:147]
	v_mfma_f32_16x16x32_bf16 v[132:135], v[88:91], v[210:213], v[132:135]
	v_mfma_f32_16x16x32_bf16 v[128:131], v[188:191], v[210:213], v[128:131]
	v_mfma_f32_16x16x32_bf16 v[116:119], v[88:91], v[218:221], v[116:119]
	v_mfma_f32_16x16x32_bf16 v[112:115], v[188:191], v[218:221], v[112:115]
	v_mfma_f32_16x16x32_bf16 v[96:99], v[88:91], v[226:229], v[96:99]
	v_mfma_f32_16x16x32_bf16 v[92:95], v[188:191], v[226:229], v[92:95]
	v_mfma_f32_16x16x32_bf16 v[148:151], v[100:103], v[206:209], v[148:151]
	v_mfma_f32_16x16x32_bf16 v[144:147], v[192:195], v[206:209], v[144:147]
	v_mfma_f32_16x16x32_bf16 v[132:135], v[100:103], v[214:217], v[132:135]
	v_mfma_f32_16x16x32_bf16 v[128:131], v[192:195], v[214:217], v[128:131]
	v_mfma_f32_16x16x32_bf16 v[116:119], v[100:103], v[222:225], v[116:119]
	v_mfma_f32_16x16x32_bf16 v[112:115], v[192:195], v[222:225], v[112:115]
	v_mfma_f32_16x16x32_bf16 v[96:99], v[100:103], v[230:233], v[96:99]
	v_mfma_f32_16x16x32_bf16 v[92:95], v[192:195], v[230:233], v[92:95]
	s_setprio 0
	s_barrier
	s_add_i32 s27, s54, s38
	v_lshl_add_u64 v[240:241], v[238:239], 0, v[168:169]
	s_mov_b32 m0, s27
	ds_read_b128 v[196:199], v205 offset:16384
	ds_read_b128 v[206:209], v205 offset:17408
	ds_read_b128 v[210:213], v205 offset:18432
	ds_read_b128 v[214:217], v205 offset:19456
	ds_read_b128 v[218:221], v205 offset:20480
	ds_read_b128 v[222:225], v205 offset:21504
	ds_read_b128 v[226:229], v205 offset:22528
	ds_read_b128 v[230:233], v205 offset:23552
	global_load_lds_dwordx4 v[240:241], off
	v_lshl_add_u64 v[242:243], v[238:239], 0, v[172:173]
	s_add_i32 m0, s27, 0x2000
	v_lshl_add_u64 v[244:245], v[238:239], 0, s[10:11]
	s_add_i32 s27, s55, s38
	global_load_lds_dwordx4 v[242:243], off
	v_lshl_add_u64 v[246:247], v[244:245], 0, v[168:169]
	s_mov_b32 m0, s27
	v_lshl_add_u64 v[244:245], v[244:245], 0, v[172:173]
	global_load_lds_dwordx4 v[246:247], off
	s_add_i32 m0, s27, 0x2000
	v_lshl_add_u64 v[246:247], v[236:237], 0, v[170:171]
	global_load_lds_dwordx4 v[244:245], off
	v_lshl_add_u64 v[244:245], v[236:237], 0, v[166:167]
	s_waitcnt vmcnt(6)
	s_waitcnt lgkmcnt(0)
	s_barrier
	s_setprio 1
	s_waitcnt lgkmcnt(0)
	v_mfma_f32_16x16x32_bf16 v[80:83], v[64:67], v[196:199], v[80:83]
	v_mfma_f32_16x16x32_bf16 v[76:79], v[72:75], v[196:199], v[76:79]
	v_mfma_f32_16x16x32_bf16 v[44:47], v[64:67], v[210:213], v[44:47]
	v_mfma_f32_16x16x32_bf16 v[40:43], v[72:75], v[210:213], v[40:43]
	v_mfma_f32_16x16x32_bf16 v[28:31], v[64:67], v[218:221], v[28:31]
	v_mfma_f32_16x16x32_bf16 v[24:27], v[72:75], v[218:221], v[24:27]
	v_mfma_f32_16x16x32_bf16 v[12:15], v[64:67], v[226:229], v[12:15]
	v_mfma_f32_16x16x32_bf16 v[8:11], v[72:75], v[226:229], v[8:11]
	v_mfma_f32_16x16x32_bf16 v[80:83], v[68:71], v[206:209], v[80:83]
	v_mfma_f32_16x16x32_bf16 v[76:79], v[84:87], v[206:209], v[76:79]
	v_mfma_f32_16x16x32_bf16 v[44:47], v[68:71], v[214:217], v[44:47]
	v_mfma_f32_16x16x32_bf16 v[40:43], v[84:87], v[214:217], v[40:43]
	v_mfma_f32_16x16x32_bf16 v[28:31], v[68:71], v[222:225], v[28:31]
	v_mfma_f32_16x16x32_bf16 v[24:27], v[84:87], v[222:225], v[24:27]
	v_mfma_f32_16x16x32_bf16 v[12:15], v[68:71], v[230:233], v[12:15]
	v_mfma_f32_16x16x32_bf16 v[8:11], v[84:87], v[230:233], v[8:11]
	s_setprio 0
	s_setprio 1
	v_mfma_f32_16x16x32_bf16 v[60:63], v[88:91], v[196:199], v[60:63]
	v_mfma_f32_16x16x32_bf16 v[56:59], v[188:191], v[196:199], v[56:59]
	v_mfma_f32_16x16x32_bf16 v[36:39], v[88:91], v[210:213], v[36:39]
	v_mfma_f32_16x16x32_bf16 v[32:35], v[188:191], v[210:213], v[32:35]
	v_mfma_f32_16x16x32_bf16 v[20:23], v[88:91], v[218:221], v[20:23]
	v_mfma_f32_16x16x32_bf16 v[16:19], v[188:191], v[218:221], v[16:19]
	v_mfma_f32_16x16x32_bf16 v[4:7], v[88:91], v[226:229], v[4:7]
	v_mfma_f32_16x16x32_bf16 v[0:3], v[188:191], v[226:229], v[0:3]
	v_mfma_f32_16x16x32_bf16 v[60:63], v[100:103], v[206:209], v[60:63]
	v_mfma_f32_16x16x32_bf16 v[56:59], v[192:195], v[206:209], v[56:59]
	v_mfma_f32_16x16x32_bf16 v[36:39], v[100:103], v[214:217], v[36:39]
	v_mfma_f32_16x16x32_bf16 v[32:35], v[192:195], v[214:217], v[32:35]
	v_mfma_f32_16x16x32_bf16 v[20:23], v[100:103], v[222:225], v[20:23]
	v_mfma_f32_16x16x32_bf16 v[16:19], v[192:195], v[222:225], v[16:19]
	v_mfma_f32_16x16x32_bf16 v[4:7], v[100:103], v[230:233], v[4:7]
	v_mfma_f32_16x16x32_bf16 v[0:3], v[192:195], v[230:233], v[0:3]
	s_setprio 0
	s_barrier
	s_add_i32 s27, 0, 0x18000
	s_add_i32 s29, 0, 0x1c000
	v_add_u32_e32 v84, s27, v202
	v_add_u32_e32 v192, s29, v202
	ds_read_b128 v[64:67], v84
	ds_read_b128 v[68:71], v84 offset:1024
	ds_read_b128 v[72:75], v84 offset:2048
	ds_read_b128 v[84:87], v84 offset:3072
	ds_read_b128 v[88:91], v192
	ds_read_b128 v[100:103], v192 offset:1024
	ds_read_b128 v[188:191], v192 offset:2048
	ds_read_b128 v[192:195], v192 offset:3072
	v_lshl_add_u64 v[236:237], v[236:237], 0, s[10:11]
	s_mov_b32 m0, s41
	v_lshl_add_u64 v[248:249], v[236:237], 0, v[166:167]
	ds_read_b128 v[196:199], v205 offset:32768
	ds_read_b128 v[206:209], v205 offset:33792
	ds_read_b128 v[210:213], v205 offset:34816
	ds_read_b128 v[214:217], v205 offset:35840
	ds_read_b128 v[218:221], v205 offset:36864
	ds_read_b128 v[222:225], v205 offset:37888
	ds_read_b128 v[226:229], v205 offset:38912
	ds_read_b128 v[230:233], v205 offset:39936
	s_mov_b32 m0, s39
	s_nop 0
	global_load_lds_dwordx4 v[244:245], off
	s_mov_b32 m0, s40
	s_nop 0
	global_load_lds_dwordx4 v[246:247], off
	s_mov_b32 m0, s41
	s_nop 0
	global_load_lds_dwordx4 v[248:249], off
	v_lshl_add_u64 v[236:237], v[236:237], 0, v[170:171]
	s_mov_b32 m0, s42
	s_nop 0
	global_load_lds_dwordx4 v[236:237], off
	s_waitcnt vmcnt(8)
	s_waitcnt lgkmcnt(0)
	s_barrier
	s_setprio 1
	s_waitcnt lgkmcnt(0)
	v_mfma_f32_16x16x32_bf16 v[156:159], v[64:67], v[196:199], v[156:159]
	v_mfma_f32_16x16x32_bf16 v[152:155], v[72:75], v[196:199], v[152:155]
	v_mfma_f32_16x16x32_bf16 v[140:143], v[64:67], v[210:213], v[140:143]
	v_mfma_f32_16x16x32_bf16 v[136:139], v[72:75], v[210:213], v[136:139]
	v_mfma_f32_16x16x32_bf16 v[124:127], v[64:67], v[218:221], v[124:127]
	v_mfma_f32_16x16x32_bf16 v[120:123], v[72:75], v[218:221], v[120:123]
	v_mfma_f32_16x16x32_bf16 v[108:111], v[64:67], v[226:229], v[108:111]
	v_mfma_f32_16x16x32_bf16 v[104:107], v[72:75], v[226:229], v[104:107]
	v_mfma_f32_16x16x32_bf16 v[156:159], v[68:71], v[206:209], v[156:159]
	v_mfma_f32_16x16x32_bf16 v[152:155], v[84:87], v[206:209], v[152:155]
	v_mfma_f32_16x16x32_bf16 v[140:143], v[68:71], v[214:217], v[140:143]
	v_mfma_f32_16x16x32_bf16 v[136:139], v[84:87], v[214:217], v[136:139]
	v_mfma_f32_16x16x32_bf16 v[124:127], v[68:71], v[222:225], v[124:127]
	v_mfma_f32_16x16x32_bf16 v[120:123], v[84:87], v[222:225], v[120:123]
	v_mfma_f32_16x16x32_bf16 v[108:111], v[68:71], v[230:233], v[108:111]
	v_mfma_f32_16x16x32_bf16 v[104:107], v[84:87], v[230:233], v[104:107]
	s_setprio 0
	s_setprio 1
	v_mfma_f32_16x16x32_bf16 v[148:151], v[88:91], v[196:199], v[148:151]
	v_mfma_f32_16x16x32_bf16 v[144:147], v[188:191], v[196:199], v[144:147]
	v_mfma_f32_16x16x32_bf16 v[132:135], v[88:91], v[210:213], v[132:135]
	v_mfma_f32_16x16x32_bf16 v[128:131], v[188:191], v[210:213], v[128:131]
	v_mfma_f32_16x16x32_bf16 v[116:119], v[88:91], v[218:221], v[116:119]
	v_mfma_f32_16x16x32_bf16 v[112:115], v[188:191], v[218:221], v[112:115]
	v_mfma_f32_16x16x32_bf16 v[96:99], v[88:91], v[226:229], v[96:99]
	v_mfma_f32_16x16x32_bf16 v[92:95], v[188:191], v[226:229], v[92:95]
	v_mfma_f32_16x16x32_bf16 v[148:151], v[100:103], v[206:209], v[148:151]
	v_mfma_f32_16x16x32_bf16 v[144:147], v[192:195], v[206:209], v[144:147]
	v_mfma_f32_16x16x32_bf16 v[132:135], v[100:103], v[214:217], v[132:135]
	v_mfma_f32_16x16x32_bf16 v[128:131], v[192:195], v[214:217], v[128:131]
	v_mfma_f32_16x16x32_bf16 v[116:119], v[100:103], v[222:225], v[116:119]
	v_mfma_f32_16x16x32_bf16 v[112:115], v[192:195], v[222:225], v[112:115]
	v_mfma_f32_16x16x32_bf16 v[96:99], v[100:103], v[230:233], v[96:99]
	v_mfma_f32_16x16x32_bf16 v[92:95], v[192:195], v[230:233], v[92:95]
	s_setprio 0
	s_barrier
	s_add_i32 s27, s27, s38
	v_lshl_add_u64 v[236:237], v[240:241], 0, s[16:17]
	s_mov_b32 m0, s27
	ds_read_b128 v[196:199], v205 offset:49152
	ds_read_b128 v[206:209], v205 offset:50176
	ds_read_b128 v[210:213], v205 offset:51200
	ds_read_b128 v[214:217], v205 offset:52224
	ds_read_b128 v[218:221], v205 offset:53248
	ds_read_b128 v[222:225], v205 offset:54272
	ds_read_b128 v[226:229], v205 offset:55296
	ds_read_b128 v[230:233], v205 offset:56320
	global_load_lds_dwordx4 v[236:237], off
	v_lshl_add_u64 v[236:237], v[242:243], 0, s[16:17]
	s_add_i32 m0, s27, 0x2000
	s_add_i32 s27, s29, s38
	global_load_lds_dwordx4 v[236:237], off
	v_lshl_add_u64 v[236:237], v[238:239], 0, s[18:19]
	v_lshl_add_u64 v[238:239], v[236:237], 0, v[168:169]
	s_mov_b32 m0, s27
	v_lshl_add_u64 v[236:237], v[236:237], 0, v[172:173]
	global_load_lds_dwordx4 v[238:239], off
	s_add_i32 m0, s27, 0x2000
	s_nop 0
	global_load_lds_dwordx4 v[236:237], off
	v_lshl_add_u64 v[236:237], v[244:245], 0, s[16:17]
	s_mov_b32 m0, s44
	s_nop 0
	global_load_lds_dwordx4 v[236:237], off
	v_lshl_add_u64 v[236:237], v[246:247], 0, s[16:17]
	s_mov_b32 m0, s45
	s_nop 0
	global_load_lds_dwordx4 v[236:237], off
	s_waitcnt vmcnt(8)
	s_waitcnt lgkmcnt(0)
	s_barrier
	s_setprio 1
	s_waitcnt lgkmcnt(0)
	v_mfma_f32_16x16x32_bf16 v[80:83], v[64:67], v[196:199], v[80:83]
	v_mfma_f32_16x16x32_bf16 v[76:79], v[72:75], v[196:199], v[76:79]
	v_mfma_f32_16x16x32_bf16 v[44:47], v[64:67], v[210:213], v[44:47]
	v_mfma_f32_16x16x32_bf16 v[40:43], v[72:75], v[210:213], v[40:43]
	v_mfma_f32_16x16x32_bf16 v[28:31], v[64:67], v[218:221], v[28:31]
	v_mfma_f32_16x16x32_bf16 v[24:27], v[72:75], v[218:221], v[24:27]
	v_mfma_f32_16x16x32_bf16 v[12:15], v[64:67], v[226:229], v[12:15]
	v_mfma_f32_16x16x32_bf16 v[8:11], v[72:75], v[226:229], v[8:11]
	v_mfma_f32_16x16x32_bf16 v[80:83], v[68:71], v[206:209], v[80:83]
	v_mfma_f32_16x16x32_bf16 v[76:79], v[84:87], v[206:209], v[76:79]
	v_mfma_f32_16x16x32_bf16 v[44:47], v[68:71], v[214:217], v[44:47]
	v_mfma_f32_16x16x32_bf16 v[40:43], v[84:87], v[214:217], v[40:43]
	v_mfma_f32_16x16x32_bf16 v[28:31], v[68:71], v[222:225], v[28:31]
	v_mfma_f32_16x16x32_bf16 v[24:27], v[84:87], v[222:225], v[24:27]
	v_mfma_f32_16x16x32_bf16 v[12:15], v[68:71], v[230:233], v[12:15]
	v_mfma_f32_16x16x32_bf16 v[8:11], v[84:87], v[230:233], v[8:11]
	s_setprio 0
	s_setprio 1
	v_mfma_f32_16x16x32_bf16 v[60:63], v[88:91], v[196:199], v[60:63]
	v_mfma_f32_16x16x32_bf16 v[56:59], v[188:191], v[196:199], v[56:59]
	v_mfma_f32_16x16x32_bf16 v[36:39], v[88:91], v[210:213], v[36:39]
	v_mfma_f32_16x16x32_bf16 v[32:35], v[188:191], v[210:213], v[32:35]
	v_mfma_f32_16x16x32_bf16 v[20:23], v[88:91], v[218:221], v[20:23]
	v_mfma_f32_16x16x32_bf16 v[16:19], v[188:191], v[218:221], v[16:19]
	v_mfma_f32_16x16x32_bf16 v[4:7], v[88:91], v[226:229], v[4:7]
	v_mfma_f32_16x16x32_bf16 v[0:3], v[188:191], v[226:229], v[0:3]
	v_mfma_f32_16x16x32_bf16 v[60:63], v[100:103], v[206:209], v[60:63]
	v_mfma_f32_16x16x32_bf16 v[56:59], v[192:195], v[206:209], v[56:59]
	v_mfma_f32_16x16x32_bf16 v[36:39], v[100:103], v[214:217], v[36:39]
	v_mfma_f32_16x16x32_bf16 v[32:35], v[192:195], v[214:217], v[32:35]
	v_mfma_f32_16x16x32_bf16 v[20:23], v[100:103], v[222:225], v[20:23]
	v_mfma_f32_16x16x32_bf16 v[16:19], v[192:195], v[222:225], v[16:19]
	v_mfma_f32_16x16x32_bf16 v[4:7], v[100:103], v[230:233], v[4:7]
	v_mfma_f32_16x16x32_bf16 v[0:3], v[192:195], v[230:233], v[0:3]
	s_setprio 0
	s_barrier
	s_add_i32 s9, s9, 2
	v_lshl_add_u64 v[52:53], v[52:53], 0, s[22:23]
	s_cmp_gt_u32 s9, 13
	v_lshl_add_u64 v[54:55], v[54:55], 0, s[22:23]
	s_cbranch_scc0 .LBB0_698
	s_and_b64 vcc, exec, s[20:21]
	s_cbranch_vccz .LBB0_701
	s_barrier

.LBB0_872:
	ds_read_b128 v[164:167], v155
	ds_read_b128 v[168:171], v155 offset:1024
	ds_read_b128 v[172:175], v155 offset:2048
	ds_read_b128 v[176:179], v155 offset:3072
	ds_read_b128 v[180:183], v156
	ds_read_b128 v[188:191], v156 offset:1024
	ds_read_b128 v[192:195], v156 offset:2048
	ds_read_b128 v[196:199], v156 offset:3072
	s_add_u32 s50, s34, 0xfffc0080
	s_addc_u32 s51, s35, -1
	s_cmp_eq_u32 s23, 12
	s_cselect_b64 vcc, -1, 0
	s_and_b64 s[36:37], vcc, exec
	v_cndmask_b32_e32 v159, v151, v149, vcc
	s_cselect_b32 s37, s21, s51
	s_cselect_b32 s36, s25, s50
	v_cndmask_b32_e32 v158, v150, v148, vcc
	v_lshl_add_u64 v[232:233], s[34:35], 0, v[138:139]
	s_add_i32 m0, s29, 0xc000
	ds_read_b128 v[200:203], v157
	ds_read_b128 v[204:207], v157 offset:1024
	ds_read_b128 v[208:211], v157 offset:2048
	ds_read_b128 v[212:215], v157 offset:3072
	ds_read_b128 v[216:219], v157 offset:4096
	ds_read_b128 v[220:223], v157 offset:5120
	ds_read_b128 v[224:227], v157 offset:6144
	ds_read_b128 v[228:231], v157 offset:7168
	global_load_lds_dwordx4 v[232:233], off
	v_lshl_add_u64 v[232:233], s[34:35], 0, v[140:141]
	s_add_i32 m0, s29, 0xe000
	s_nop 0
	global_load_lds_dwordx4 v[232:233], off
	s_waitcnt vmcnt(8)
	s_waitcnt lgkmcnt(0)
	s_barrier
	s_setprio 1
	s_waitcnt lgkmcnt(0)
	v_mfma_f32_16x16x32_bf16 v[124:127], v[164:167], v[200:203], v[124:127]
	v_mfma_f32_16x16x32_bf16 v[120:123], v[172:175], v[200:203], v[120:123]
	v_mfma_f32_16x16x32_bf16 v[112:115], v[164:167], v[208:211], v[112:115]
	v_mfma_f32_16x16x32_bf16 v[104:107], v[172:175], v[208:211], v[104:107]
	v_mfma_f32_16x16x32_bf16 v[92:95], v[164:167], v[216:219], v[92:95]
	v_mfma_f32_16x16x32_bf16 v[88:91], v[172:175], v[216:219], v[88:91]
	v_mfma_f32_16x16x32_bf16 v[84:87], v[164:167], v[224:227], v[84:87]
	v_mfma_f32_16x16x32_bf16 v[80:83], v[172:175], v[224:227], v[80:83]
	v_mfma_f32_16x16x32_bf16 v[124:127], v[168:171], v[204:207], v[124:127]
	v_mfma_f32_16x16x32_bf16 v[120:123], v[176:179], v[204:207], v[120:123]
	v_mfma_f32_16x16x32_bf16 v[112:115], v[168:171], v[212:215], v[112:115]
	v_mfma_f32_16x16x32_bf16 v[104:107], v[176:179], v[212:215], v[104:107]
	v_mfma_f32_16x16x32_bf16 v[92:95], v[168:171], v[220:223], v[92:95]
	v_mfma_f32_16x16x32_bf16 v[88:91], v[176:179], v[220:223], v[88:91]
	v_mfma_f32_16x16x32_bf16 v[84:87], v[168:171], v[228:231], v[84:87]
	v_mfma_f32_16x16x32_bf16 v[80:83], v[176:179], v[228:231], v[80:83]
	s_setprio 0
	s_setprio 1
	v_mfma_f32_16x16x32_bf16 v[116:119], v[180:183], v[200:203], v[116:119]
	v_mfma_f32_16x16x32_bf16 v[108:111], v[192:195], v[200:203], v[108:111]
	v_mfma_f32_16x16x32_bf16 v[100:103], v[180:183], v[208:211], v[100:103]
	v_mfma_f32_16x16x32_bf16 v[96:99], v[192:195], v[208:211], v[96:99]
	v_mfma_f32_16x16x32_bf16 v[76:79], v[180:183], v[216:219], v[76:79]
	v_mfma_f32_16x16x32_bf16 v[72:75], v[192:195], v[216:219], v[72:75]
	v_mfma_f32_16x16x32_bf16 v[68:71], v[180:183], v[224:227], v[68:71]
	v_mfma_f32_16x16x32_bf16 v[64:67], v[192:195], v[224:227], v[64:67]
	v_mfma_f32_16x16x32_bf16 v[116:119], v[188:191], v[204:207], v[116:119]
	v_mfma_f32_16x16x32_bf16 v[108:111], v[196:199], v[204:207], v[108:111]
	v_mfma_f32_16x16x32_bf16 v[100:103], v[188:191], v[212:215], v[100:103]
	v_mfma_f32_16x16x32_bf16 v[96:99], v[196:199], v[212:215], v[96:99]
	v_mfma_f32_16x16x32_bf16 v[76:79], v[188:191], v[220:223], v[76:79]
	v_mfma_f32_16x16x32_bf16 v[72:75], v[196:199], v[220:223], v[72:75]
	v_mfma_f32_16x16x32_bf16 v[68:71], v[188:191], v[228:231], v[68:71]
	v_mfma_f32_16x16x32_bf16 v[64:67], v[196:199], v[228:231], v[64:67]
	s_setprio 0
	s_barrier
	s_add_i32 s50, s48, s33
	v_lshl_add_u64 v[232:233], v[158:159], 0, v[134:135]
	s_mov_b32 m0, s50
	ds_read_b128 v[200:203], v157 offset:16384
	ds_read_b128 v[204:207], v157 offset:17408
	ds_read_b128 v[208:211], v157 offset:18432
	ds_read_b128 v[212:215], v157 offset:19456
	ds_read_b128 v[216:219], v157 offset:20480
	ds_read_b128 v[220:223], v157 offset:21504
	ds_read_b128 v[224:227], v157 offset:22528
	ds_read_b128 v[228:231], v157 offset:23552
	global_load_lds_dwordx4 v[232:233], off
	v_lshl_add_u64 v[236:237], v[158:159], 0, v[130:131]
	s_add_i32 m0, s50, 0x2000
	v_lshl_add_u64 v[238:239], v[158:159], 0, s[8:9]
	s_add_i32 s50, s49, s33
	global_load_lds_dwordx4 v[236:237], off
	v_lshl_add_u64 v[240:241], v[238:239], 0, v[134:135]
	s_mov_b32 m0, s50
	v_lshl_add_u64 v[238:239], v[238:239], 0, v[130:131]
	global_load_lds_dwordx4 v[240:241], off
	s_add_i32 m0, s50, 0x2000
	v_lshl_add_u64 v[240:241], s[36:37], 0, v[132:133]
	global_load_lds_dwordx4 v[238:239], off
	v_lshl_add_u64 v[238:239], s[36:37], 0, v[136:137]
	s_waitcnt vmcnt(6)
	s_waitcnt lgkmcnt(0)
	s_barrier
	s_setprio 1
	s_waitcnt lgkmcnt(0)
	s_cmp_eq_u32 s40, 2
	s_cbranch_scc0 .Lm0_kfull_a
	s_cmp_eq_u32 s46, 0x100
	s_cbranch_scc1 .Lm0_kskip_a

.Lm0_kskip_a:
	s_setprio 0
	s_barrier
	s_add_i32 s50, 0, 0x18000
	s_add_i32 s51, 0, 0x1c000
	v_add_u32_e32 v176, s50, v154
	v_add_u32_e32 v196, s51, v154
	ds_read_b128 v[164:167], v176
	ds_read_b128 v[168:171], v176 offset:1024
	ds_read_b128 v[172:175], v176 offset:2048
	ds_read_b128 v[176:179], v176 offset:3072
	ds_read_b128 v[180:183], v196
	ds_read_b128 v[188:191], v196 offset:1024
	ds_read_b128 v[192:195], v196 offset:2048
	ds_read_b128 v[196:199], v196 offset:3072
	s_add_u32 s36, s36, 0x40000
	s_addc_u32 s37, s37, 0
	s_mov_b32 m0, s38
	v_lshl_add_u64 v[242:243], s[36:37], 0, v[136:137]
	ds_read_b128 v[200:203], v157 offset:32768
	ds_read_b128 v[204:207], v157 offset:33792
	ds_read_b128 v[208:211], v157 offset:34816
	ds_read_b128 v[212:215], v157 offset:35840
	ds_read_b128 v[216:219], v157 offset:36864
	ds_read_b128 v[220:223], v157 offset:37888
	ds_read_b128 v[224:227], v157 offset:38912
	ds_read_b128 v[228:231], v157 offset:39936
	s_mov_b32 m0, s29
	s_nop 0
	global_load_lds_dwordx4 v[238:239], off
	s_mov_b32 m0, s31
	s_nop 0
	global_load_lds_dwordx4 v[240:241], off
	s_mov_b32 m0, s38
	s_nop 0
	global_load_lds_dwordx4 v[242:243], off
	v_lshl_add_u64 v[242:243], s[36:37], 0, v[132:133]
	s_mov_b32 m0, s39
	s_nop 0
	global_load_lds_dwordx4 v[242:243], off
	s_waitcnt vmcnt(8)
	s_waitcnt lgkmcnt(0)
	s_barrier
	s_setprio 1
	s_waitcnt lgkmcnt(0)
	v_mfma_f32_16x16x32_bf16 v[124:127], v[164:167], v[200:203], v[124:127]
	v_mfma_f32_16x16x32_bf16 v[120:123], v[172:175], v[200:203], v[120:123]
	v_mfma_f32_16x16x32_bf16 v[112:115], v[164:167], v[208:211], v[112:115]
	v_mfma_f32_16x16x32_bf16 v[104:107], v[172:175], v[208:211], v[104:107]
	v_mfma_f32_16x16x32_bf16 v[92:95], v[164:167], v[216:219], v[92:95]
	v_mfma_f32_16x16x32_bf16 v[88:91], v[172:175], v[216:219], v[88:91]
	v_mfma_f32_16x16x32_bf16 v[84:87], v[164:167], v[224:227], v[84:87]
	v_mfma_f32_16x16x32_bf16 v[80:83], v[172:175], v[224:227], v[80:83]
	v_mfma_f32_16x16x32_bf16 v[124:127], v[168:171], v[204:207], v[124:127]
	v_mfma_f32_16x16x32_bf16 v[120:123], v[176:179], v[204:207], v[120:123]
	v_mfma_f32_16x16x32_bf16 v[112:115], v[168:171], v[212:215], v[112:115]
	v_mfma_f32_16x16x32_bf16 v[104:107], v[176:179], v[212:215], v[104:107]
	v_mfma_f32_16x16x32_bf16 v[92:95], v[168:171], v[220:223], v[92:95]
	v_mfma_f32_16x16x32_bf16 v[88:91], v[176:179], v[220:223], v[88:91]
	v_mfma_f32_16x16x32_bf16 v[84:87], v[168:171], v[228:231], v[84:87]
	v_mfma_f32_16x16x32_bf16 v[80:83], v[176:179], v[228:231], v[80:83]
	s_setprio 0
	s_setprio 1
	v_mfma_f32_16x16x32_bf16 v[116:119], v[180:183], v[200:203], v[116:119]
	v_mfma_f32_16x16x32_bf16 v[108:111], v[192:195], v[200:203], v[108:111]
	v_mfma_f32_16x16x32_bf16 v[100:103], v[180:183], v[208:211], v[100:103]
	v_mfma_f32_16x16x32_bf16 v[96:99], v[192:195], v[208:211], v[96:99]
	v_mfma_f32_16x16x32_bf16 v[76:79], v[180:183], v[216:219], v[76:79]
	v_mfma_f32_16x16x32_bf16 v[72:75], v[192:195], v[216:219], v[72:75]
	v_mfma_f32_16x16x32_bf16 v[68:71], v[180:183], v[224:227], v[68:71]
	v_mfma_f32_16x16x32_bf16 v[64:67], v[192:195], v[224:227], v[64:67]
	v_mfma_f32_16x16x32_bf16 v[116:119], v[188:191], v[204:207], v[116:119]
	v_mfma_f32_16x16x32_bf16 v[108:111], v[196:199], v[204:207], v[108:111]
	v_mfma_f32_16x16x32_bf16 v[100:103], v[188:191], v[212:215], v[100:103]
	v_mfma_f32_16x16x32_bf16 v[96:99], v[196:199], v[212:215], v[96:99]
	v_mfma_f32_16x16x32_bf16 v[76:79], v[188:191], v[220:223], v[76:79]
	v_mfma_f32_16x16x32_bf16 v[72:75], v[196:199], v[220:223], v[72:75]
	v_mfma_f32_16x16x32_bf16 v[68:71], v[188:191], v[228:231], v[68:71]
	v_mfma_f32_16x16x32_bf16 v[64:67], v[196:199], v[228:231], v[64:67]
	s_setprio 0
	s_barrier
	s_add_i32 s36, s50, s33
	v_lshl_add_u64 v[232:233], v[232:233], 0, s[12:13]
	s_mov_b32 m0, s36
	ds_read_b128 v[200:203], v157 offset:49152
	ds_read_b128 v[204:207], v157 offset:50176
	ds_read_b128 v[208:211], v157 offset:51200
	ds_read_b128 v[212:215], v157 offset:52224
	ds_read_b128 v[216:219], v157 offset:53248
	ds_read_b128 v[220:223], v157 offset:54272
	ds_read_b128 v[224:227], v157 offset:55296
	ds_read_b128 v[228:231], v157 offset:56320
	global_load_lds_dwordx4 v[232:233], off
	v_lshl_add_u64 v[232:233], v[236:237], 0, s[12:13]
	s_add_i32 m0, s36, 0x2000
	v_lshl_add_u64 v[158:159], v[158:159], 0, s[14:15]
	s_add_i32 s36, s51, s33
	global_load_lds_dwordx4 v[232:233], off
	v_lshl_add_u64 v[232:233], v[158:159], 0, v[134:135]
	s_mov_b32 m0, s36
	v_lshl_add_u64 v[158:159], v[158:159], 0, v[130:131]
	global_load_lds_dwordx4 v[232:233], off
	s_add_i32 m0, s36, 0x2000
	s_nop 0
	global_load_lds_dwordx4 v[158:159], off
	v_lshl_add_u64 v[158:159], v[238:239], 0, s[12:13]
	s_mov_b32 m0, s41
	s_nop 0
	global_load_lds_dwordx4 v[158:159], off
	v_lshl_add_u64 v[158:159], v[240:241], 0, s[12:13]
	s_mov_b32 m0, s42
	s_nop 0
	global_load_lds_dwordx4 v[158:159], off
	s_waitcnt vmcnt(8)
	s_waitcnt lgkmcnt(0)
	s_barrier
	s_setprio 1
	s_waitcnt lgkmcnt(0)
	s_cmp_eq_u32 s40, 2
	s_cbranch_scc0 .Lm0_kfull_b
	s_cmp_eq_u32 s46, 0x100
	s_cbranch_scc1 .Lm0_kskip_b

.LBB0_888:
	ds_read_b128 v[164:167], v155
	ds_read_b128 v[168:171], v155 offset:1024
	ds_read_b128 v[172:175], v155 offset:2048
	ds_read_b128 v[176:179], v155 offset:3072
	ds_read_b128 v[180:183], v156
	ds_read_b128 v[188:191], v156 offset:1024
	ds_read_b128 v[192:195], v156 offset:2048
	ds_read_b128 v[196:199], v156 offset:3072
	s_add_u32 s53, s34, 0xfffc0080
	s_addc_u32 s54, s35, -1
	s_cmp_eq_u32 s23, 12
	s_cselect_b64 vcc, -1, 0
	s_and_b64 s[36:37], vcc, exec
	v_cndmask_b32_e32 v159, v151, v149, vcc
	s_cselect_b32 s37, s21, s54
	s_cselect_b32 s36, s25, s53
	v_cndmask_b32_e32 v158, v150, v148, vcc
	v_lshl_add_u64 v[232:233], s[34:35], 0, v[138:139]
	s_add_i32 m0, s29, 0xc000
	ds_read_b128 v[200:203], v157
	ds_read_b128 v[204:207], v157 offset:1024
	ds_read_b128 v[208:211], v157 offset:2048
	ds_read_b128 v[212:215], v157 offset:3072
	ds_read_b128 v[216:219], v157 offset:4096
	ds_read_b128 v[220:223], v157 offset:5120
	ds_read_b128 v[224:227], v157 offset:6144
	ds_read_b128 v[228:231], v157 offset:7168
	global_load_lds_dwordx4 v[232:233], off
	v_lshl_add_u64 v[232:233], s[34:35], 0, v[140:141]
	s_add_i32 m0, s29, 0xe000
	s_nop 0
	global_load_lds_dwordx4 v[232:233], off
	s_waitcnt vmcnt(8)
	s_waitcnt lgkmcnt(0)
	s_barrier
	s_setprio 1
	s_waitcnt lgkmcnt(0)
	v_mfma_f32_16x16x32_bf16 v[124:127], v[164:167], v[200:203], v[124:127]
	v_mfma_f32_16x16x32_bf16 v[120:123], v[172:175], v[200:203], v[120:123]
	v_mfma_f32_16x16x32_bf16 v[108:111], v[164:167], v[208:211], v[108:111]
	v_mfma_f32_16x16x32_bf16 v[104:107], v[172:175], v[208:211], v[104:107]
	v_mfma_f32_16x16x32_bf16 v[92:95], v[164:167], v[216:219], v[92:95]
	v_mfma_f32_16x16x32_bf16 v[88:91], v[172:175], v[216:219], v[88:91]
	v_mfma_f32_16x16x32_bf16 v[76:79], v[164:167], v[224:227], v[76:79]
	v_mfma_f32_16x16x32_bf16 v[72:75], v[172:175], v[224:227], v[72:75]
	v_mfma_f32_16x16x32_bf16 v[124:127], v[168:171], v[204:207], v[124:127]
	v_mfma_f32_16x16x32_bf16 v[120:123], v[176:179], v[204:207], v[120:123]
	v_mfma_f32_16x16x32_bf16 v[108:111], v[168:171], v[212:215], v[108:111]
	v_mfma_f32_16x16x32_bf16 v[104:107], v[176:179], v[212:215], v[104:107]
	v_mfma_f32_16x16x32_bf16 v[92:95], v[168:171], v[220:223], v[92:95]
	v_mfma_f32_16x16x32_bf16 v[88:91], v[176:179], v[220:223], v[88:91]
	v_mfma_f32_16x16x32_bf16 v[76:79], v[168:171], v[228:231], v[76:79]
	v_mfma_f32_16x16x32_bf16 v[72:75], v[176:179], v[228:231], v[72:75]
	s_setprio 0
	s_setprio 1
	v_mfma_f32_16x16x32_bf16 v[116:119], v[180:183], v[200:203], v[116:119]
	v_mfma_f32_16x16x32_bf16 v[112:115], v[192:195], v[200:203], v[112:115]
	v_mfma_f32_16x16x32_bf16 v[100:103], v[180:183], v[208:211], v[100:103]
	v_mfma_f32_16x16x32_bf16 v[96:99], v[192:195], v[208:211], v[96:99]
	v_mfma_f32_16x16x32_bf16 v[84:87], v[180:183], v[216:219], v[84:87]
	v_mfma_f32_16x16x32_bf16 v[80:83], v[192:195], v[216:219], v[80:83]
	v_mfma_f32_16x16x32_bf16 v[68:71], v[180:183], v[224:227], v[68:71]
	v_mfma_f32_16x16x32_bf16 v[64:67], v[192:195], v[224:227], v[64:67]
	v_mfma_f32_16x16x32_bf16 v[116:119], v[188:191], v[204:207], v[116:119]
	v_mfma_f32_16x16x32_bf16 v[112:115], v[196:199], v[204:207], v[112:115]
	v_mfma_f32_16x16x32_bf16 v[100:103], v[188:191], v[212:215], v[100:103]
	v_mfma_f32_16x16x32_bf16 v[96:99], v[196:199], v[212:215], v[96:99]
	v_mfma_f32_16x16x32_bf16 v[84:87], v[188:191], v[220:223], v[84:87]
	v_mfma_f32_16x16x32_bf16 v[80:83], v[196:199], v[220:223], v[80:83]
	v_mfma_f32_16x16x32_bf16 v[68:71], v[188:191], v[228:231], v[68:71]
	v_mfma_f32_16x16x32_bf16 v[64:67], v[196:199], v[228:231], v[64:67]
	s_setprio 0
	s_barrier
	s_add_i32 s53, s50, s33
	v_lshl_add_u64 v[232:233], v[158:159], 0, v[134:135]
	s_mov_b32 m0, s53
	ds_read_b128 v[200:203], v157 offset:16384
	ds_read_b128 v[204:207], v157 offset:17408
	ds_read_b128 v[208:211], v157 offset:18432
	ds_read_b128 v[212:215], v157 offset:19456
	ds_read_b128 v[216:219], v157 offset:20480
	ds_read_b128 v[220:223], v157 offset:21504
	ds_read_b128 v[224:227], v157 offset:22528
	ds_read_b128 v[228:231], v157 offset:23552
	global_load_lds_dwordx4 v[232:233], off
	v_lshl_add_u64 v[236:237], v[158:159], 0, v[130:131]
	s_add_i32 m0, s53, 0x2000
	v_lshl_add_u64 v[238:239], v[158:159], 0, s[8:9]
	s_add_i32 s53, s51, s33
	global_load_lds_dwordx4 v[236:237], off
	v_lshl_add_u64 v[240:241], v[238:239], 0, v[134:135]
	s_mov_b32 m0, s53
	v_lshl_add_u64 v[238:239], v[238:239], 0, v[130:131]
	global_load_lds_dwordx4 v[240:241], off
	s_add_i32 m0, s53, 0x2000
	v_lshl_add_u64 v[240:241], s[36:37], 0, v[132:133]
	global_load_lds_dwordx4 v[238:239], off
	v_lshl_add_u64 v[238:239], s[36:37], 0, v[136:137]
	s_waitcnt vmcnt(6)
	s_waitcnt lgkmcnt(0)
	s_barrier
	s_setprio 1
	s_waitcnt lgkmcnt(0)
	s_cmp_eq_u32 s42, 2
	s_cbranch_scc0 .Lm1_kfull_a
	s_cmp_eq_u32 s48, 0x100
	s_cbranch_scc1 .Lm1_kskip_a

.Lm1_kskip_a:
	s_setprio 0
	s_barrier
	s_add_i32 s53, 0, 0x18000
	s_add_i32 s54, 0, 0x1c000
	v_add_u32_e32 v176, s53, v154
	v_add_u32_e32 v196, s54, v154
	ds_read_b128 v[164:167], v176
	ds_read_b128 v[168:171], v176 offset:1024
	ds_read_b128 v[172:175], v176 offset:2048
	ds_read_b128 v[176:179], v176 offset:3072
	ds_read_b128 v[180:183], v196
	ds_read_b128 v[188:191], v196 offset:1024
	ds_read_b128 v[192:195], v196 offset:2048
	ds_read_b128 v[196:199], v196 offset:3072
	s_add_u32 s36, s36, 0x40000
	s_addc_u32 s37, s37, 0
	s_mov_b32 m0, s40
	v_lshl_add_u64 v[242:243], s[36:37], 0, v[136:137]
	ds_read_b128 v[200:203], v157 offset:32768
	ds_read_b128 v[204:207], v157 offset:33792
	ds_read_b128 v[208:211], v157 offset:34816
	ds_read_b128 v[212:215], v157 offset:35840
	ds_read_b128 v[216:219], v157 offset:36864
	ds_read_b128 v[220:223], v157 offset:37888
	ds_read_b128 v[224:227], v157 offset:38912
	ds_read_b128 v[228:231], v157 offset:39936
	s_mov_b32 m0, s29
	s_nop 0
	global_load_lds_dwordx4 v[238:239], off
	s_mov_b32 m0, s31
	s_nop 0
	global_load_lds_dwordx4 v[240:241], off
	s_mov_b32 m0, s40
	s_nop 0
	global_load_lds_dwordx4 v[242:243], off
	v_lshl_add_u64 v[242:243], s[36:37], 0, v[132:133]
	s_mov_b32 m0, s41
	s_nop 0
	global_load_lds_dwordx4 v[242:243], off
	s_waitcnt vmcnt(8)
	s_waitcnt lgkmcnt(0)
	s_barrier
	s_setprio 1
	s_waitcnt lgkmcnt(0)
	v_mfma_f32_16x16x32_bf16 v[124:127], v[164:167], v[200:203], v[124:127]
	v_mfma_f32_16x16x32_bf16 v[120:123], v[172:175], v[200:203], v[120:123]
	v_mfma_f32_16x16x32_bf16 v[108:111], v[164:167], v[208:211], v[108:111]
	v_mfma_f32_16x16x32_bf16 v[104:107], v[172:175], v[208:211], v[104:107]
	v_mfma_f32_16x16x32_bf16 v[92:95], v[164:167], v[216:219], v[92:95]
	v_mfma_f32_16x16x32_bf16 v[88:91], v[172:175], v[216:219], v[88:91]
	v_mfma_f32_16x16x32_bf16 v[76:79], v[164:167], v[224:227], v[76:79]
	v_mfma_f32_16x16x32_bf16 v[72:75], v[172:175], v[224:227], v[72:75]
	v_mfma_f32_16x16x32_bf16 v[124:127], v[168:171], v[204:207], v[124:127]
	v_mfma_f32_16x16x32_bf16 v[120:123], v[176:179], v[204:207], v[120:123]
	v_mfma_f32_16x16x32_bf16 v[108:111], v[168:171], v[212:215], v[108:111]
	v_mfma_f32_16x16x32_bf16 v[104:107], v[176:179], v[212:215], v[104:107]
	v_mfma_f32_16x16x32_bf16 v[92:95], v[168:171], v[220:223], v[92:95]
	v_mfma_f32_16x16x32_bf16 v[88:91], v[176:179], v[220:223], v[88:91]
	v_mfma_f32_16x16x32_bf16 v[76:79], v[168:171], v[228:231], v[76:79]
	v_mfma_f32_16x16x32_bf16 v[72:75], v[176:179], v[228:231], v[72:75]
	s_setprio 0
	s_setprio 1
	v_mfma_f32_16x16x32_bf16 v[116:119], v[180:183], v[200:203], v[116:119]
	v_mfma_f32_16x16x32_bf16 v[112:115], v[192:195], v[200:203], v[112:115]
	v_mfma_f32_16x16x32_bf16 v[100:103], v[180:183], v[208:211], v[100:103]
	v_mfma_f32_16x16x32_bf16 v[96:99], v[192:195], v[208:211], v[96:99]
	v_mfma_f32_16x16x32_bf16 v[84:87], v[180:183], v[216:219], v[84:87]
	v_mfma_f32_16x16x32_bf16 v[80:83], v[192:195], v[216:219], v[80:83]
	v_mfma_f32_16x16x32_bf16 v[68:71], v[180:183], v[224:227], v[68:71]
	v_mfma_f32_16x16x32_bf16 v[64:67], v[192:195], v[224:227], v[64:67]
	v_mfma_f32_16x16x32_bf16 v[116:119], v[188:191], v[204:207], v[116:119]
	v_mfma_f32_16x16x32_bf16 v[112:115], v[196:199], v[204:207], v[112:115]
	v_mfma_f32_16x16x32_bf16 v[100:103], v[188:191], v[212:215], v[100:103]
	v_mfma_f32_16x16x32_bf16 v[96:99], v[196:199], v[212:215], v[96:99]
	v_mfma_f32_16x16x32_bf16 v[84:87], v[188:191], v[220:223], v[84:87]
	v_mfma_f32_16x16x32_bf16 v[80:83], v[196:199], v[220:223], v[80:83]
	v_mfma_f32_16x16x32_bf16 v[68:71], v[188:191], v[228:231], v[68:71]
	v_mfma_f32_16x16x32_bf16 v[64:67], v[196:199], v[228:231], v[64:67]
	s_setprio 0
	s_barrier
	s_add_i32 s36, s53, s33
	v_lshl_add_u64 v[232:233], v[232:233], 0, s[12:13]
	s_mov_b32 m0, s36
	ds_read_b128 v[200:203], v157 offset:49152
	ds_read_b128 v[204:207], v157 offset:50176
	ds_read_b128 v[208:211], v157 offset:51200
	ds_read_b128 v[212:215], v157 offset:52224
	ds_read_b128 v[216:219], v157 offset:53248
	ds_read_b128 v[220:223], v157 offset:54272
	ds_read_b128 v[224:227], v157 offset:55296
	ds_read_b128 v[228:231], v157 offset:56320
	global_load_lds_dwordx4 v[232:233], off
	v_lshl_add_u64 v[232:233], v[236:237], 0, s[12:13]
	s_add_i32 m0, s36, 0x2000
	v_lshl_add_u64 v[158:159], v[158:159], 0, s[14:15]
	s_add_i32 s36, s54, s33
	global_load_lds_dwordx4 v[232:233], off
	v_lshl_add_u64 v[232:233], v[158:159], 0, v[134:135]
	s_mov_b32 m0, s36
	v_lshl_add_u64 v[158:159], v[158:159], 0, v[130:131]
	global_load_lds_dwordx4 v[232:233], off
	s_add_i32 m0, s36, 0x2000
	s_nop 0
	global_load_lds_dwordx4 v[158:159], off
	v_lshl_add_u64 v[158:159], v[238:239], 0, s[12:13]
	s_mov_b32 m0, s43
	s_nop 0
	global_load_lds_dwordx4 v[158:159], off
	v_lshl_add_u64 v[158:159], v[240:241], 0, s[12:13]
	s_mov_b32 m0, s44
	s_nop 0
	global_load_lds_dwordx4 v[158:159], off
	s_waitcnt vmcnt(8)
	s_waitcnt lgkmcnt(0)
	s_barrier
	s_setprio 1
	s_waitcnt lgkmcnt(0)
	s_cmp_eq_u32 s42, 2
	s_cbranch_scc0 .Lm1_kfull_b
	s_cmp_eq_u32 s48, 0x100
	s_cbranch_scc1 .Lm1_kskip_b

.LBB0_958:
	v_add_u32_e32 v164, s82, v237
	ds_read_b128 v[56:59], v239
	ds_read_b128 v[60:63], v239 offset:1024
	ds_read_b128 v[144:147], v239 offset:2048
	ds_read_b128 v[148:151], v239 offset:3072
	ds_read_b128 v[152:155], v164
	ds_read_b128 v[156:159], v164 offset:1024
	ds_read_b128 v[160:163], v164 offset:2048
	ds_read_b128 v[164:167], v164 offset:3072
	s_cmp_eq_u32 s7, 12
	v_lshl_add_u64 v[168:169], v[44:45], 0, s[36:37]
	s_cselect_b64 vcc, -1, 0
	v_cndmask_b32_e32 v241, v169, v41, vcc
	v_cndmask_b32_e32 v240, v168, v40, vcc
	v_cndmask_b32_e32 v243, v47, v43, vcc
	v_cndmask_b32_e32 v242, v46, v42, vcc
	v_lshl_add_u64 v[244:245], v[44:45], 0, v[208:209]
	s_add_i32 m0, s69, 0xc000
	ds_read_b128 v[168:171], v238
	ds_read_b128 v[172:175], v238 offset:1024
	ds_read_b128 v[176:179], v238 offset:2048
	ds_read_b128 v[180:183], v238 offset:3072
	ds_read_b128 v[218:221], v238 offset:4096
	ds_read_b128 v[222:225], v238 offset:5120
	ds_read_b128 v[226:229], v238 offset:6144
	ds_read_b128 v[230:233], v238 offset:7168
	global_load_lds_dwordx4 v[244:245], off
	v_lshl_add_u64 v[244:245], v[44:45], 0, v[210:211]
	s_add_i32 m0, s69, 0xe000
	s_nop 0
	global_load_lds_dwordx4 v[244:245], off
	s_waitcnt vmcnt(8)
	s_waitcnt lgkmcnt(0)
	s_barrier
	s_setprio 1
	s_waitcnt lgkmcnt(0)
	v_mfma_f32_16x16x32_bf16 v[140:143], v[56:59], v[168:171], v[140:143]
	v_mfma_f32_16x16x32_bf16 v[136:139], v[144:147], v[168:171], v[136:139]
	v_mfma_f32_16x16x32_bf16 v[124:127], v[56:59], v[176:179], v[124:127]
	v_mfma_f32_16x16x32_bf16 v[120:123], v[144:147], v[176:179], v[120:123]
	v_mfma_f32_16x16x32_bf16 v[108:111], v[56:59], v[218:221], v[108:111]
	v_mfma_f32_16x16x32_bf16 v[104:107], v[144:147], v[218:221], v[104:107]
	v_mfma_f32_16x16x32_bf16 v[92:95], v[56:59], v[226:229], v[92:95]
	v_mfma_f32_16x16x32_bf16 v[88:91], v[144:147], v[226:229], v[88:91]
	v_mfma_f32_16x16x32_bf16 v[140:143], v[60:63], v[172:175], v[140:143]
	v_mfma_f32_16x16x32_bf16 v[136:139], v[148:151], v[172:175], v[136:139]
	v_mfma_f32_16x16x32_bf16 v[124:127], v[60:63], v[180:183], v[124:127]
	v_mfma_f32_16x16x32_bf16 v[120:123], v[148:151], v[180:183], v[120:123]
	v_mfma_f32_16x16x32_bf16 v[108:111], v[60:63], v[222:225], v[108:111]
	v_mfma_f32_16x16x32_bf16 v[104:107], v[148:151], v[222:225], v[104:107]
	v_mfma_f32_16x16x32_bf16 v[92:95], v[60:63], v[230:233], v[92:95]
	v_mfma_f32_16x16x32_bf16 v[88:91], v[148:151], v[230:233], v[88:91]
	s_setprio 0
	s_setprio 1
	v_mfma_f32_16x16x32_bf16 v[132:135], v[152:155], v[168:171], v[132:135]
	v_mfma_f32_16x16x32_bf16 v[128:131], v[160:163], v[168:171], v[128:131]
	v_mfma_f32_16x16x32_bf16 v[116:119], v[152:155], v[176:179], v[116:119]
	v_mfma_f32_16x16x32_bf16 v[112:115], v[160:163], v[176:179], v[112:115]
	v_mfma_f32_16x16x32_bf16 v[100:103], v[152:155], v[218:221], v[100:103]
	v_mfma_f32_16x16x32_bf16 v[96:99], v[160:163], v[218:221], v[96:99]
	v_mfma_f32_16x16x32_bf16 v[84:87], v[152:155], v[226:229], v[84:87]
	v_mfma_f32_16x16x32_bf16 v[80:83], v[160:163], v[226:229], v[80:83]
	v_mfma_f32_16x16x32_bf16 v[132:135], v[156:159], v[172:175], v[132:135]
	v_mfma_f32_16x16x32_bf16 v[128:131], v[164:167], v[172:175], v[128:131]
	v_mfma_f32_16x16x32_bf16 v[116:119], v[156:159], v[180:183], v[116:119]
	v_mfma_f32_16x16x32_bf16 v[112:115], v[164:167], v[180:183], v[112:115]
	v_mfma_f32_16x16x32_bf16 v[100:103], v[156:159], v[222:225], v[100:103]
	v_mfma_f32_16x16x32_bf16 v[96:99], v[164:167], v[222:225], v[96:99]
	v_mfma_f32_16x16x32_bf16 v[84:87], v[156:159], v[230:233], v[84:87]
	v_mfma_f32_16x16x32_bf16 v[80:83], v[164:167], v[230:233], v[80:83]
	s_setprio 0
	s_barrier
	s_add_i32 s8, s81, s68
	v_lshl_add_u64 v[244:245], v[242:243], 0, v[192:193]
	s_mov_b32 m0, s8
	ds_read_b128 v[168:171], v238 offset:16384
	ds_read_b128 v[172:175], v238 offset:17408
	ds_read_b128 v[176:179], v238 offset:18432
	ds_read_b128 v[180:183], v238 offset:19456
	ds_read_b128 v[218:221], v238 offset:20480
	ds_read_b128 v[222:225], v238 offset:21504
	ds_read_b128 v[226:229], v238 offset:22528
	ds_read_b128 v[230:233], v238 offset:23552
	global_load_lds_dwordx4 v[244:245], off
	v_lshl_add_u64 v[246:247], v[242:243], 0, v[196:197]
	s_add_i32 m0, s8, 0x2000
	v_lshl_add_u64 v[248:249], v[242:243], 0, s[16:17]
	s_add_i32 s8, s82, s68
	global_load_lds_dwordx4 v[246:247], off
	v_lshl_add_u64 v[250:251], v[248:249], 0, v[192:193]
	s_mov_b32 m0, s8
	v_lshl_add_u64 v[248:249], v[248:249], 0, v[196:197]
	global_load_lds_dwordx4 v[250:251], off
	s_add_i32 m0, s8, 0x2000
	v_lshl_add_u64 v[250:251], v[240:241], 0, v[194:195]
	global_load_lds_dwordx4 v[248:249], off
	v_lshl_add_u64 v[248:249], v[240:241], 0, v[190:191]
	s_waitcnt vmcnt(6)
	s_waitcnt lgkmcnt(0)
	s_barrier
	s_setprio 1
	s_waitcnt lgkmcnt(0)
	s_cmp_eq_u32 s84, 2
	s_cbranch_scc0 .Lwo_half_full_a
	s_cmp_eq_u32 s79, 0x100
	s_cbranch_scc1 .Lwo_half_skip_a

.Lwo_half_skip_a:
	s_setprio 0
	s_barrier
	s_add_i32 s8, 0, 0x18000
	s_add_i32 s9, 0, 0x1c000
	v_add_u32_e32 v148, s8, v237
	v_add_u32_e32 v164, s9, v237
	ds_read_b128 v[64:67], v148
	ds_read_b128 v[68:71], v148 offset:1024
	ds_read_b128 v[144:147], v148 offset:2048
	ds_read_b128 v[148:151], v148 offset:3072
	ds_read_b128 v[152:155], v164
	ds_read_b128 v[156:159], v164 offset:1024
	ds_read_b128 v[160:163], v164 offset:2048
	ds_read_b128 v[164:167], v164 offset:3072
	v_lshl_add_u64 v[240:241], v[240:241], 0, s[16:17]
	s_mov_b32 m0, s71
	v_lshl_add_u64 v[252:253], v[240:241], 0, v[190:191]
	ds_read_b128 v[168:171], v238 offset:32768
	ds_read_b128 v[172:175], v238 offset:33792
	ds_read_b128 v[176:179], v238 offset:34816
	ds_read_b128 v[180:183], v238 offset:35840
	ds_read_b128 v[218:221], v238 offset:36864
	ds_read_b128 v[222:225], v238 offset:37888
	ds_read_b128 v[226:229], v238 offset:38912
	ds_read_b128 v[230:233], v238 offset:39936
	s_mov_b32 m0, s69
	s_nop 0
	global_load_lds_dwordx4 v[248:249], off
	s_mov_b32 m0, s70
	s_nop 0
	global_load_lds_dwordx4 v[250:251], off
	s_mov_b32 m0, s71
	s_nop 0
	global_load_lds_dwordx4 v[252:253], off
	v_lshl_add_u64 v[240:241], v[240:241], 0, v[194:195]
	s_mov_b32 m0, s72
	s_nop 0
	global_load_lds_dwordx4 v[240:241], off
	s_waitcnt vmcnt(8)
	s_waitcnt lgkmcnt(0)
	s_barrier
	s_setprio 1
	s_waitcnt lgkmcnt(0)
	v_mfma_f32_16x16x32_bf16 v[140:143], v[64:67], v[168:171], v[140:143]
	v_mfma_f32_16x16x32_bf16 v[136:139], v[144:147], v[168:171], v[136:139]
	v_mfma_f32_16x16x32_bf16 v[124:127], v[64:67], v[176:179], v[124:127]
	v_mfma_f32_16x16x32_bf16 v[120:123], v[144:147], v[176:179], v[120:123]
	v_mfma_f32_16x16x32_bf16 v[108:111], v[64:67], v[218:221], v[108:111]
	v_mfma_f32_16x16x32_bf16 v[104:107], v[144:147], v[218:221], v[104:107]
	v_mfma_f32_16x16x32_bf16 v[92:95], v[64:67], v[226:229], v[92:95]
	v_mfma_f32_16x16x32_bf16 v[88:91], v[144:147], v[226:229], v[88:91]
	v_mfma_f32_16x16x32_bf16 v[140:143], v[68:71], v[172:175], v[140:143]
	v_mfma_f32_16x16x32_bf16 v[136:139], v[148:151], v[172:175], v[136:139]
	v_mfma_f32_16x16x32_bf16 v[124:127], v[68:71], v[180:183], v[124:127]
	v_mfma_f32_16x16x32_bf16 v[120:123], v[148:151], v[180:183], v[120:123]
	v_mfma_f32_16x16x32_bf16 v[108:111], v[68:71], v[222:225], v[108:111]
	v_mfma_f32_16x16x32_bf16 v[104:107], v[148:151], v[222:225], v[104:107]
	v_mfma_f32_16x16x32_bf16 v[92:95], v[68:71], v[230:233], v[92:95]
	v_mfma_f32_16x16x32_bf16 v[88:91], v[148:151], v[230:233], v[88:91]
	s_setprio 0
	s_setprio 1
	v_mfma_f32_16x16x32_bf16 v[132:135], v[152:155], v[168:171], v[132:135]
	v_mfma_f32_16x16x32_bf16 v[128:131], v[160:163], v[168:171], v[128:131]
	v_mfma_f32_16x16x32_bf16 v[116:119], v[152:155], v[176:179], v[116:119]
	v_mfma_f32_16x16x32_bf16 v[112:115], v[160:163], v[176:179], v[112:115]
	v_mfma_f32_16x16x32_bf16 v[100:103], v[152:155], v[218:221], v[100:103]
	v_mfma_f32_16x16x32_bf16 v[96:99], v[160:163], v[218:221], v[96:99]
	v_mfma_f32_16x16x32_bf16 v[84:87], v[152:155], v[226:229], v[84:87]
	v_mfma_f32_16x16x32_bf16 v[80:83], v[160:163], v[226:229], v[80:83]
	v_mfma_f32_16x16x32_bf16 v[132:135], v[156:159], v[172:175], v[132:135]
	v_mfma_f32_16x16x32_bf16 v[128:131], v[164:167], v[172:175], v[128:131]
	v_mfma_f32_16x16x32_bf16 v[116:119], v[156:159], v[180:183], v[116:119]
	v_mfma_f32_16x16x32_bf16 v[112:115], v[164:167], v[180:183], v[112:115]
	v_mfma_f32_16x16x32_bf16 v[100:103], v[156:159], v[222:225], v[100:103]
	v_mfma_f32_16x16x32_bf16 v[96:99], v[164:167], v[222:225], v[96:99]
	v_mfma_f32_16x16x32_bf16 v[84:87], v[156:159], v[230:233], v[84:87]
	v_mfma_f32_16x16x32_bf16 v[80:83], v[164:167], v[230:233], v[80:83]
	s_setprio 0
	s_barrier
	s_add_i32 s8, s8, s68
	v_lshl_add_u64 v[240:241], v[244:245], 0, s[26:27]
	s_mov_b32 m0, s8
	ds_read_b128 v[168:171], v238 offset:49152
	ds_read_b128 v[172:175], v238 offset:50176
	ds_read_b128 v[176:179], v238 offset:51200
	ds_read_b128 v[180:183], v238 offset:52224
	ds_read_b128 v[218:221], v238 offset:53248
	ds_read_b128 v[222:225], v238 offset:54272
	ds_read_b128 v[226:229], v238 offset:55296
	ds_read_b128 v[230:233], v238 offset:56320
	global_load_lds_dwordx4 v[240:241], off
	v_lshl_add_u64 v[240:241], v[246:247], 0, s[26:27]
	s_add_i32 m0, s8, 0x2000
	s_add_i32 s8, s9, s68
	global_load_lds_dwordx4 v[240:241], off
	v_lshl_add_u64 v[240:241], v[242:243], 0, s[28:29]
	v_lshl_add_u64 v[242:243], v[240:241], 0, v[192:193]
	s_mov_b32 m0, s8
	v_lshl_add_u64 v[240:241], v[240:241], 0, v[196:197]
	global_load_lds_dwordx4 v[242:243], off
	s_add_i32 m0, s8, 0x2000
	s_nop 0
	global_load_lds_dwordx4 v[240:241], off
	v_lshl_add_u64 v[240:241], v[248:249], 0, s[26:27]
	s_mov_b32 m0, s73
	s_nop 0
	global_load_lds_dwordx4 v[240:241], off
	v_lshl_add_u64 v[240:241], v[250:251], 0, s[26:27]
	s_mov_b32 m0, s74
	s_nop 0
	global_load_lds_dwordx4 v[240:241], off
	s_waitcnt vmcnt(8)
	s_waitcnt lgkmcnt(0)
	s_barrier
	s_setprio 1
	s_waitcnt lgkmcnt(0)
	s_cmp_eq_u32 s84, 2
	s_cbranch_scc0 .Lwo_half_full_b
	s_cmp_eq_u32 s79, 0x100
	s_cbranch_scc1 .Lwo_half_skip_b

.LBB0_1106:
	ds_read_b128 v[128:131], v185
	ds_read_b128 v[132:135], v185 offset:1024
	ds_read_b128 v[136:139], v185 offset:2048
	ds_read_b128 v[140:143], v185 offset:3072
	ds_read_b128 v[144:147], v189
	ds_read_b128 v[148:151], v189 offset:1024
	ds_read_b128 v[176:179], v189 offset:2048
	ds_read_b128 v[190:193], v189 offset:3072
	s_add_u32 s38, s36, 0xfffc0080
	s_addc_u32 s39, s37, -1
	s_cmp_eq_u32 s60, 12
	s_cselect_b32 s41, s7, s39
	s_cselect_b32 s40, s25, s38
	s_cselect_b32 s39, s27, s47
	s_cselect_b32 s38, s29, s46
	v_lshl_add_u64 v[168:169], s[36:37], 0, v[160:161]
	s_add_i32 m0, s48, 0xc000
	ds_read_b128 v[196:199], v195
	ds_read_b128 v[200:203], v195 offset:1024
	ds_read_b128 v[204:207], v195 offset:2048
	ds_read_b128 v[208:211], v195 offset:3072
	ds_read_b128 v[212:215], v195 offset:4096
	ds_read_b128 v[216:219], v195 offset:5120
	ds_read_b128 v[220:223], v195 offset:6144
	ds_read_b128 v[224:227], v195 offset:7168
	global_load_lds_dwordx4 v[168:169], off
	v_lshl_add_u64 v[168:169], s[36:37], 0, v[162:163]
	s_add_i32 m0, s48, 0xe000
	s_nop 0
	global_load_lds_dwordx4 v[168:169], off
	s_waitcnt vmcnt(8)
	s_waitcnt lgkmcnt(0)
	s_barrier
	s_setprio 1
	s_waitcnt lgkmcnt(0)
	v_mfma_f32_16x16x32_bf16 v[124:127], v[128:131], v[196:199], v[124:127]
	v_mfma_f32_16x16x32_bf16 v[120:123], v[136:139], v[196:199], v[120:123]
	v_mfma_f32_16x16x32_bf16 v[108:111], v[128:131], v[204:207], v[108:111]
	v_mfma_f32_16x16x32_bf16 v[104:107], v[136:139], v[204:207], v[104:107]
	v_mfma_f32_16x16x32_bf16 v[92:95], v[128:131], v[212:215], v[92:95]
	v_mfma_f32_16x16x32_bf16 v[88:91], v[136:139], v[212:215], v[88:91]
	v_mfma_f32_16x16x32_bf16 v[76:79], v[128:131], v[220:223], v[76:79]
	v_mfma_f32_16x16x32_bf16 v[72:75], v[136:139], v[220:223], v[72:75]
	v_mfma_f32_16x16x32_bf16 v[124:127], v[132:135], v[200:203], v[124:127]
	v_mfma_f32_16x16x32_bf16 v[120:123], v[140:143], v[200:203], v[120:123]
	v_mfma_f32_16x16x32_bf16 v[108:111], v[132:135], v[208:211], v[108:111]
	v_mfma_f32_16x16x32_bf16 v[104:107], v[140:143], v[208:211], v[104:107]
	v_mfma_f32_16x16x32_bf16 v[92:95], v[132:135], v[216:219], v[92:95]
	v_mfma_f32_16x16x32_bf16 v[88:91], v[140:143], v[216:219], v[88:91]
	v_mfma_f32_16x16x32_bf16 v[76:79], v[132:135], v[224:227], v[76:79]
	v_mfma_f32_16x16x32_bf16 v[72:75], v[140:143], v[224:227], v[72:75]
	s_setprio 0
	s_setprio 1
	v_mfma_f32_16x16x32_bf16 v[116:119], v[144:147], v[196:199], v[116:119]
	v_mfma_f32_16x16x32_bf16 v[112:115], v[176:179], v[196:199], v[112:115]
	v_mfma_f32_16x16x32_bf16 v[100:103], v[144:147], v[204:207], v[100:103]
	v_mfma_f32_16x16x32_bf16 v[96:99], v[176:179], v[204:207], v[96:99]
	v_mfma_f32_16x16x32_bf16 v[84:87], v[144:147], v[212:215], v[84:87]
	v_mfma_f32_16x16x32_bf16 v[80:83], v[176:179], v[212:215], v[80:83]
	v_mfma_f32_16x16x32_bf16 v[68:71], v[144:147], v[220:223], v[68:71]
	v_mfma_f32_16x16x32_bf16 v[64:67], v[176:179], v[220:223], v[64:67]
	v_mfma_f32_16x16x32_bf16 v[116:119], v[148:151], v[200:203], v[116:119]
	v_mfma_f32_16x16x32_bf16 v[112:115], v[190:193], v[200:203], v[112:115]
	v_mfma_f32_16x16x32_bf16 v[100:103], v[148:151], v[208:211], v[100:103]
	v_mfma_f32_16x16x32_bf16 v[96:99], v[190:193], v[208:211], v[96:99]
	v_mfma_f32_16x16x32_bf16 v[84:87], v[148:151], v[216:219], v[84:87]
	v_mfma_f32_16x16x32_bf16 v[80:83], v[190:193], v[216:219], v[80:83]
	v_mfma_f32_16x16x32_bf16 v[68:71], v[148:151], v[224:227], v[68:71]
	v_mfma_f32_16x16x32_bf16 v[64:67], v[190:193], v[224:227], v[64:67]
	s_setprio 0
	s_barrier
	s_add_i32 s61, s66, s43
	v_lshl_add_u64 v[168:169], s[38:39], 0, v[156:157]
	s_mov_b32 m0, s61
	ds_read_b128 v[196:199], v195 offset:16384
	ds_read_b128 v[200:203], v195 offset:17408
	ds_read_b128 v[204:207], v195 offset:18432
	ds_read_b128 v[208:211], v195 offset:19456
	ds_read_b128 v[212:215], v195 offset:20480
	ds_read_b128 v[216:219], v195 offset:21504
	ds_read_b128 v[220:223], v195 offset:22528
	ds_read_b128 v[224:227], v195 offset:23552
	global_load_lds_dwordx4 v[168:169], off
	s_add_i32 m0, s61, 0x2000
	s_add_u32 s70, s38, 0x40000
	v_lshl_add_u64 v[172:173], s[38:39], 0, v[152:153]
	s_addc_u32 s71, s39, 0
	s_add_i32 s61, s67, s43
	global_load_lds_dwordx4 v[172:173], off
	v_lshl_add_u64 v[180:181], s[70:71], 0, v[156:157]
	s_mov_b32 m0, s61
	v_lshl_add_u64 v[186:187], s[40:41], 0, v[154:155]
	global_load_lds_dwordx4 v[180:181], off
	v_lshl_add_u64 v[180:181], s[70:71], 0, v[152:153]
	s_add_i32 m0, s61, 0x2000
	s_nop 0
	global_load_lds_dwordx4 v[180:181], off
	v_lshl_add_u64 v[180:181], s[40:41], 0, v[158:159]
	s_waitcnt vmcnt(6)
	s_waitcnt lgkmcnt(0)
	s_barrier
	s_setprio 1
	s_waitcnt lgkmcnt(0)
	v_mfma_f32_16x16x32_bf16 v[60:63], v[128:131], v[196:199], v[60:63]
	v_mfma_f32_16x16x32_bf16 v[56:59], v[136:139], v[196:199], v[56:59]
	v_mfma_f32_16x16x32_bf16 v[44:47], v[128:131], v[204:207], v[44:47]
	v_mfma_f32_16x16x32_bf16 v[40:43], v[136:139], v[204:207], v[40:43]
	v_mfma_f32_16x16x32_bf16 v[28:31], v[128:131], v[212:215], v[28:31]
	v_mfma_f32_16x16x32_bf16 v[24:27], v[136:139], v[212:215], v[24:27]
	v_mfma_f32_16x16x32_bf16 v[12:15], v[128:131], v[220:223], v[12:15]
	v_mfma_f32_16x16x32_bf16 v[8:11], v[136:139], v[220:223], v[8:11]
	v_mfma_f32_16x16x32_bf16 v[60:63], v[132:135], v[200:203], v[60:63]
	v_mfma_f32_16x16x32_bf16 v[56:59], v[140:143], v[200:203], v[56:59]
	v_mfma_f32_16x16x32_bf16 v[44:47], v[132:135], v[208:211], v[44:47]
	v_mfma_f32_16x16x32_bf16 v[40:43], v[140:143], v[208:211], v[40:43]
	v_mfma_f32_16x16x32_bf16 v[28:31], v[132:135], v[216:219], v[28:31]
	v_mfma_f32_16x16x32_bf16 v[24:27], v[140:143], v[216:219], v[24:27]
	v_mfma_f32_16x16x32_bf16 v[12:15], v[132:135], v[224:227], v[12:15]
	v_mfma_f32_16x16x32_bf16 v[8:11], v[140:143], v[224:227], v[8:11]
	s_setprio 0
	s_setprio 1
	v_mfma_f32_16x16x32_bf16 v[52:55], v[144:147], v[196:199], v[52:55]
	v_mfma_f32_16x16x32_bf16 v[48:51], v[176:179], v[196:199], v[48:51]
	v_mfma_f32_16x16x32_bf16 v[36:39], v[144:147], v[204:207], v[36:39]
	v_mfma_f32_16x16x32_bf16 v[32:35], v[176:179], v[204:207], v[32:35]
	v_mfma_f32_16x16x32_bf16 v[20:23], v[144:147], v[212:215], v[20:23]
	v_mfma_f32_16x16x32_bf16 v[16:19], v[176:179], v[212:215], v[16:19]
	v_mfma_f32_16x16x32_bf16 v[4:7], v[144:147], v[220:223], v[4:7]
	v_mfma_f32_16x16x32_bf16 v[0:3], v[176:179], v[220:223], v[0:3]
	v_mfma_f32_16x16x32_bf16 v[52:55], v[148:151], v[200:203], v[52:55]
	v_mfma_f32_16x16x32_bf16 v[48:51], v[190:193], v[200:203], v[48:51]
	v_mfma_f32_16x16x32_bf16 v[36:39], v[148:151], v[208:211], v[36:39]
	v_mfma_f32_16x16x32_bf16 v[32:35], v[190:193], v[208:211], v[32:35]
	v_mfma_f32_16x16x32_bf16 v[20:23], v[148:151], v[216:219], v[20:23]
	v_mfma_f32_16x16x32_bf16 v[16:19], v[190:193], v[216:219], v[16:19]
	v_mfma_f32_16x16x32_bf16 v[4:7], v[148:151], v[224:227], v[4:7]
	v_mfma_f32_16x16x32_bf16 v[0:3], v[190:193], v[224:227], v[0:3]
	s_setprio 0
	s_barrier
	s_add_i32 s61, 0, 0x18000
	s_add_i32 s70, 0, 0x1c000
	v_add_u32_e32 v140, s61, v183
	v_add_u32_e32 v170, s70, v183
	ds_read_b128 v[128:131], v140
	ds_read_b128 v[132:135], v140 offset:1024
	ds_read_b128 v[136:139], v140 offset:2048
	ds_read_b128 v[140:143], v140 offset:3072
	ds_read_b128 v[144:147], v170
	ds_read_b128 v[148:151], v170 offset:1024
	ds_read_b128 v[176:179], v170 offset:2048
	ds_read_b128 v[190:193], v170 offset:3072
	s_add_u32 s40, s40, 0x40000
	s_addc_u32 s41, s41, 0
	s_mov_b32 m0, s50
	v_lshl_add_u64 v[228:229], s[40:41], 0, v[158:159]
	ds_read_b128 v[196:199], v195 offset:32768
	ds_read_b128 v[200:203], v195 offset:33792
	ds_read_b128 v[204:207], v195 offset:34816
	ds_read_b128 v[208:211], v195 offset:35840
	ds_read_b128 v[212:215], v195 offset:36864
	ds_read_b128 v[216:219], v195 offset:37888
	ds_read_b128 v[220:223], v195 offset:38912
	ds_read_b128 v[224:227], v195 offset:39936
	s_mov_b32 m0, s48
	s_nop 0
	global_load_lds_dwordx4 v[180:181], off
	s_mov_b32 m0, s49
	s_nop 0
	global_load_lds_dwordx4 v[186:187], off
	s_mov_b32 m0, s50
	s_nop 0
	global_load_lds_dwordx4 v[228:229], off
	v_lshl_add_u64 v[228:229], s[40:41], 0, v[154:155]
	s_mov_b32 m0, s51
	s_nop 0
	global_load_lds_dwordx4 v[228:229], off
	s_waitcnt vmcnt(8)
	s_waitcnt lgkmcnt(0)
	s_barrier
	s_setprio 1
	s_waitcnt lgkmcnt(0)
	v_mfma_f32_16x16x32_bf16 v[124:127], v[128:131], v[196:199], v[124:127]
	v_mfma_f32_16x16x32_bf16 v[120:123], v[136:139], v[196:199], v[120:123]
	v_mfma_f32_16x16x32_bf16 v[108:111], v[128:131], v[204:207], v[108:111]
	v_mfma_f32_16x16x32_bf16 v[104:107], v[136:139], v[204:207], v[104:107]
	v_mfma_f32_16x16x32_bf16 v[92:95], v[128:131], v[212:215], v[92:95]
	v_mfma_f32_16x16x32_bf16 v[88:91], v[136:139], v[212:215], v[88:91]
	v_mfma_f32_16x16x32_bf16 v[76:79], v[128:131], v[220:223], v[76:79]
	v_mfma_f32_16x16x32_bf16 v[72:75], v[136:139], v[220:223], v[72:75]
	v_mfma_f32_16x16x32_bf16 v[124:127], v[132:135], v[200:203], v[124:127]
	v_mfma_f32_16x16x32_bf16 v[120:123], v[140:143], v[200:203], v[120:123]
	v_mfma_f32_16x16x32_bf16 v[108:111], v[132:135], v[208:211], v[108:111]
	v_mfma_f32_16x16x32_bf16 v[104:107], v[140:143], v[208:211], v[104:107]
	v_mfma_f32_16x16x32_bf16 v[92:95], v[132:135], v[216:219], v[92:95]
	v_mfma_f32_16x16x32_bf16 v[88:91], v[140:143], v[216:219], v[88:91]
	v_mfma_f32_16x16x32_bf16 v[76:79], v[132:135], v[224:227], v[76:79]
	v_mfma_f32_16x16x32_bf16 v[72:75], v[140:143], v[224:227], v[72:75]
	s_setprio 0
	s_setprio 1
	v_mfma_f32_16x16x32_bf16 v[116:119], v[144:147], v[196:199], v[116:119]
	v_mfma_f32_16x16x32_bf16 v[112:115], v[176:179], v[196:199], v[112:115]
	v_mfma_f32_16x16x32_bf16 v[100:103], v[144:147], v[204:207], v[100:103]
	v_mfma_f32_16x16x32_bf16 v[96:99], v[176:179], v[204:207], v[96:99]
	v_mfma_f32_16x16x32_bf16 v[84:87], v[144:147], v[212:215], v[84:87]
	v_mfma_f32_16x16x32_bf16 v[80:83], v[176:179], v[212:215], v[80:83]
	v_mfma_f32_16x16x32_bf16 v[68:71], v[144:147], v[220:223], v[68:71]
	v_mfma_f32_16x16x32_bf16 v[64:67], v[176:179], v[220:223], v[64:67]
	v_mfma_f32_16x16x32_bf16 v[116:119], v[148:151], v[200:203], v[116:119]
	v_mfma_f32_16x16x32_bf16 v[112:115], v[190:193], v[200:203], v[112:115]
	v_mfma_f32_16x16x32_bf16 v[100:103], v[148:151], v[208:211], v[100:103]
	v_mfma_f32_16x16x32_bf16 v[96:99], v[190:193], v[208:211], v[96:99]
	v_mfma_f32_16x16x32_bf16 v[84:87], v[148:151], v[216:219], v[84:87]
	v_mfma_f32_16x16x32_bf16 v[80:83], v[190:193], v[216:219], v[80:83]
	v_mfma_f32_16x16x32_bf16 v[68:71], v[148:151], v[224:227], v[68:71]
	v_mfma_f32_16x16x32_bf16 v[64:67], v[190:193], v[224:227], v[64:67]
	s_setprio 0
	s_barrier
	s_add_i32 s40, s61, s43
	v_lshl_add_u64 v[168:169], v[168:169], 0, s[16:17]
	s_mov_b32 m0, s40
	ds_read_b128 v[196:199], v195 offset:49152
	ds_read_b128 v[200:203], v195 offset:50176
	ds_read_b128 v[204:207], v195 offset:51200
	ds_read_b128 v[208:211], v195 offset:52224
	ds_read_b128 v[212:215], v195 offset:53248
	ds_read_b128 v[216:219], v195 offset:54272
	ds_read_b128 v[220:223], v195 offset:55296
	ds_read_b128 v[224:227], v195 offset:56320
	global_load_lds_dwordx4 v[168:169], off
	s_add_i32 m0, s40, 0x2000
	s_add_u32 s38, s38, 0x40080
	v_lshl_add_u64 v[168:169], v[172:173], 0, s[16:17]
	s_addc_u32 s39, s39, 0
	s_add_i32 s40, s70, s43
	global_load_lds_dwordx4 v[168:169], off
	v_lshl_add_u64 v[168:169], s[38:39], 0, v[156:157]
	s_mov_b32 m0, s40
	s_nop 0
	global_load_lds_dwordx4 v[168:169], off
	v_lshl_add_u64 v[168:169], s[38:39], 0, v[152:153]
	s_add_i32 m0, s40, 0x2000
	s_nop 0
	global_load_lds_dwordx4 v[168:169], off
	v_lshl_add_u64 v[168:169], v[180:181], 0, s[16:17]
	s_mov_b32 m0, s62
	s_nop 0
	global_load_lds_dwordx4 v[168:169], off
	v_lshl_add_u64 v[168:169], v[186:187], 0, s[16:17]
	s_mov_b32 m0, s63
	s_nop 0
	global_load_lds_dwordx4 v[168:169], off
	s_waitcnt vmcnt(8)
	s_waitcnt lgkmcnt(0)
	s_barrier
	s_setprio 1
	s_waitcnt lgkmcnt(0)
	v_mfma_f32_16x16x32_bf16 v[60:63], v[128:131], v[196:199], v[60:63]
	v_mfma_f32_16x16x32_bf16 v[56:59], v[136:139], v[196:199], v[56:59]
	v_mfma_f32_16x16x32_bf16 v[44:47], v[128:131], v[204:207], v[44:47]
	v_mfma_f32_16x16x32_bf16 v[40:43], v[136:139], v[204:207], v[40:43]
	v_mfma_f32_16x16x32_bf16 v[28:31], v[128:131], v[212:215], v[28:31]
	v_mfma_f32_16x16x32_bf16 v[24:27], v[136:139], v[212:215], v[24:27]
	v_mfma_f32_16x16x32_bf16 v[12:15], v[128:131], v[220:223], v[12:15]
	v_mfma_f32_16x16x32_bf16 v[8:11], v[136:139], v[220:223], v[8:11]
	v_mfma_f32_16x16x32_bf16 v[60:63], v[132:135], v[200:203], v[60:63]
	v_mfma_f32_16x16x32_bf16 v[56:59], v[140:143], v[200:203], v[56:59]
	v_mfma_f32_16x16x32_bf16 v[44:47], v[132:135], v[208:211], v[44:47]
	v_mfma_f32_16x16x32_bf16 v[40:43], v[140:143], v[208:211], v[40:43]
	v_mfma_f32_16x16x32_bf16 v[28:31], v[132:135], v[216:219], v[28:31]
	v_mfma_f32_16x16x32_bf16 v[24:27], v[140:143], v[216:219], v[24:27]
	v_mfma_f32_16x16x32_bf16 v[12:15], v[132:135], v[224:227], v[12:15]
	v_mfma_f32_16x16x32_bf16 v[8:11], v[140:143], v[224:227], v[8:11]
	s_setprio 0
	s_setprio 1
	v_mfma_f32_16x16x32_bf16 v[52:55], v[144:147], v[196:199], v[52:55]
	v_mfma_f32_16x16x32_bf16 v[48:51], v[176:179], v[196:199], v[48:51]
	v_mfma_f32_16x16x32_bf16 v[36:39], v[144:147], v[204:207], v[36:39]
	v_mfma_f32_16x16x32_bf16 v[32:35], v[176:179], v[204:207], v[32:35]
	v_mfma_f32_16x16x32_bf16 v[20:23], v[144:147], v[212:215], v[20:23]
	v_mfma_f32_16x16x32_bf16 v[16:19], v[176:179], v[212:215], v[16:19]
	v_mfma_f32_16x16x32_bf16 v[4:7], v[144:147], v[220:223], v[4:7]
	v_mfma_f32_16x16x32_bf16 v[0:3], v[176:179], v[220:223], v[0:3]
	v_mfma_f32_16x16x32_bf16 v[52:55], v[148:151], v[200:203], v[52:55]
	v_mfma_f32_16x16x32_bf16 v[48:51], v[190:193], v[200:203], v[48:51]
	v_mfma_f32_16x16x32_bf16 v[36:39], v[148:151], v[208:211], v[36:39]
	v_mfma_f32_16x16x32_bf16 v[32:35], v[190:193], v[208:211], v[32:35]
	v_mfma_f32_16x16x32_bf16 v[20:23], v[148:151], v[216:219], v[20:23]
	v_mfma_f32_16x16x32_bf16 v[16:19], v[190:193], v[216:219], v[16:19]
	v_mfma_f32_16x16x32_bf16 v[4:7], v[148:151], v[224:227], v[4:7]
	v_mfma_f32_16x16x32_bf16 v[0:3], v[190:193], v[224:227], v[0:3]
	s_setprio 0
	s_barrier
	s_add_i32 s60, s60, 2
	s_add_u32 s36, s36, 0x100
	s_addc_u32 s37, s37, 0
	s_add_u32 s46, s46, 0x100
	s_addc_u32 s47, s47, 0
	s_cmp_gt_u32 s60, 13
	s_cbranch_scc0 .LBB0_1106
	s_and_b64 vcc, exec, s[18:19]
	s_cbranch_vccz .LBB0_1109
	s_barrier

.LBB0_1187:
	ds_read_b128 v[128:131], v187
	ds_read_b128 v[132:135], v187 offset:1024
	ds_read_b128 v[136:139], v187 offset:2048
	ds_read_b128 v[140:143], v187 offset:3072
	ds_read_b128 v[144:147], v188
	ds_read_b128 v[148:151], v188 offset:1024
	ds_read_b128 v[152:155], v188 offset:2048
	ds_read_b128 v[156:159], v188 offset:3072
	s_add_u32 s42, s40, 0xfff00080
	s_addc_u32 s43, s41, -1
	s_cmp_eq_u32 s35, 60
	s_cselect_b32 s45, s7, s43
	s_cselect_b32 s44, s6, s42
	s_cselect_b32 s43, s37, s31
	s_cselect_b32 s42, s36, s29
	v_lshl_add_u64 v[214:215], s[40:41], 0, v[168:169]
	s_add_i32 m0, s25, 0xc000
	ds_read_b128 v[176:179], v189
	ds_read_b128 v[180:183], v189 offset:1024
	ds_read_b128 v[190:193], v189 offset:2048
	ds_read_b128 v[194:197], v189 offset:3072
	ds_read_b128 v[198:201], v189 offset:4096
	ds_read_b128 v[202:205], v189 offset:5120
	ds_read_b128 v[206:209], v189 offset:6144
	ds_read_b128 v[210:213], v189 offset:7168
	global_load_lds_dwordx4 v[214:215], off
	v_lshl_add_u64 v[214:215], s[40:41], 0, v[170:171]
	s_add_i32 m0, s25, 0xe000
	s_nop 0
	global_load_lds_dwordx4 v[214:215], off
	s_waitcnt vmcnt(8)
	s_waitcnt lgkmcnt(0)
	s_barrier
	s_setprio 1
	s_waitcnt lgkmcnt(0)
	v_mfma_f32_16x16x32_bf16 v[124:127], v[128:131], v[176:179], v[124:127]
	v_mfma_f32_16x16x32_bf16 v[120:123], v[136:139], v[176:179], v[120:123]
	v_mfma_f32_16x16x32_bf16 v[116:119], v[128:131], v[190:193], v[116:119]
	v_mfma_f32_16x16x32_bf16 v[112:115], v[136:139], v[190:193], v[112:115]
	v_mfma_f32_16x16x32_bf16 v[104:107], v[128:131], v[198:201], v[104:107]
	v_mfma_f32_16x16x32_bf16 v[96:99], v[136:139], v[198:201], v[96:99]
	v_mfma_f32_16x16x32_bf16 v[88:91], v[128:131], v[206:209], v[88:91]
	v_mfma_f32_16x16x32_bf16 v[80:83], v[136:139], v[206:209], v[80:83]
	v_mfma_f32_16x16x32_bf16 v[124:127], v[132:135], v[180:183], v[124:127]
	v_mfma_f32_16x16x32_bf16 v[120:123], v[140:143], v[180:183], v[120:123]
	v_mfma_f32_16x16x32_bf16 v[116:119], v[132:135], v[194:197], v[116:119]
	v_mfma_f32_16x16x32_bf16 v[112:115], v[140:143], v[194:197], v[112:115]
	v_mfma_f32_16x16x32_bf16 v[104:107], v[132:135], v[202:205], v[104:107]
	v_mfma_f32_16x16x32_bf16 v[96:99], v[140:143], v[202:205], v[96:99]
	v_mfma_f32_16x16x32_bf16 v[88:91], v[132:135], v[210:213], v[88:91]
	v_mfma_f32_16x16x32_bf16 v[80:83], v[140:143], v[210:213], v[80:83]
	s_setprio 0
	s_setprio 1
	v_mfma_f32_16x16x32_bf16 v[108:111], v[144:147], v[176:179], v[108:111]
	v_mfma_f32_16x16x32_bf16 v[100:103], v[152:155], v[176:179], v[100:103]
	v_mfma_f32_16x16x32_bf16 v[92:95], v[144:147], v[190:193], v[92:95]
	v_mfma_f32_16x16x32_bf16 v[84:87], v[152:155], v[190:193], v[84:87]
	v_mfma_f32_16x16x32_bf16 v[76:79], v[144:147], v[198:201], v[76:79]
	v_mfma_f32_16x16x32_bf16 v[72:75], v[152:155], v[198:201], v[72:75]
	v_mfma_f32_16x16x32_bf16 v[68:71], v[144:147], v[206:209], v[68:71]
	v_mfma_f32_16x16x32_bf16 v[64:67], v[152:155], v[206:209], v[64:67]
	v_mfma_f32_16x16x32_bf16 v[108:111], v[148:151], v[180:183], v[108:111]
	v_mfma_f32_16x16x32_bf16 v[100:103], v[156:159], v[180:183], v[100:103]
	v_mfma_f32_16x16x32_bf16 v[92:95], v[148:151], v[194:197], v[92:95]
	v_mfma_f32_16x16x32_bf16 v[84:87], v[156:159], v[194:197], v[84:87]
	v_mfma_f32_16x16x32_bf16 v[76:79], v[148:151], v[202:205], v[76:79]
	v_mfma_f32_16x16x32_bf16 v[72:75], v[156:159], v[202:205], v[72:75]
	v_mfma_f32_16x16x32_bf16 v[68:71], v[148:151], v[210:213], v[68:71]
	v_mfma_f32_16x16x32_bf16 v[64:67], v[156:159], v[210:213], v[64:67]
	s_setprio 0
	s_barrier
	s_add_i32 s46, s67, s52
	v_lshl_add_u64 v[214:215], s[42:43], 0, v[162:163]
	s_mov_b32 m0, s46
	ds_read_b128 v[176:179], v189 offset:16384
	ds_read_b128 v[180:183], v189 offset:17408
	ds_read_b128 v[190:193], v189 offset:18432
	ds_read_b128 v[194:197], v189 offset:19456
	ds_read_b128 v[198:201], v189 offset:20480
	ds_read_b128 v[202:205], v189 offset:21504
	ds_read_b128 v[206:209], v189 offset:22528
	ds_read_b128 v[210:213], v189 offset:23552
	global_load_lds_dwordx4 v[214:215], off
	s_add_i32 m0, s46, 0x2000
	s_add_u32 s46, s42, 0x100000
	v_lshl_add_u64 v[216:217], s[42:43], 0, v[166:167]
	s_addc_u32 s47, s43, 0
	s_add_i32 s60, s68, s52
	global_load_lds_dwordx4 v[216:217], off
	v_lshl_add_u64 v[218:219], s[46:47], 0, v[162:163]
	s_mov_b32 m0, s60
	v_lshl_add_u64 v[220:221], s[44:45], 0, v[164:165]
	global_load_lds_dwordx4 v[218:219], off
	v_lshl_add_u64 v[218:219], s[46:47], 0, v[166:167]
	s_add_i32 m0, s60, 0x2000
	s_nop 0
	global_load_lds_dwordx4 v[218:219], off
	v_lshl_add_u64 v[218:219], s[44:45], 0, v[160:161]
	s_waitcnt vmcnt(6)
	s_waitcnt lgkmcnt(0)
	s_barrier
	s_setprio 1
	s_waitcnt lgkmcnt(0)
	v_mfma_f32_16x16x32_bf16 v[60:63], v[128:131], v[176:179], v[60:63]
	v_mfma_f32_16x16x32_bf16 v[56:59], v[136:139], v[176:179], v[56:59]
	v_mfma_f32_16x16x32_bf16 v[52:55], v[128:131], v[190:193], v[52:55]
	v_mfma_f32_16x16x32_bf16 v[48:51], v[136:139], v[190:193], v[48:51]
	v_mfma_f32_16x16x32_bf16 v[40:43], v[128:131], v[198:201], v[40:43]
	v_mfma_f32_16x16x32_bf16 v[32:35], v[136:139], v[198:201], v[32:35]
	v_mfma_f32_16x16x32_bf16 v[24:27], v[128:131], v[206:209], v[24:27]
	v_mfma_f32_16x16x32_bf16 v[16:19], v[136:139], v[206:209], v[16:19]
	v_mfma_f32_16x16x32_bf16 v[60:63], v[132:135], v[180:183], v[60:63]
	v_mfma_f32_16x16x32_bf16 v[56:59], v[140:143], v[180:183], v[56:59]
	v_mfma_f32_16x16x32_bf16 v[52:55], v[132:135], v[194:197], v[52:55]
	v_mfma_f32_16x16x32_bf16 v[48:51], v[140:143], v[194:197], v[48:51]
	v_mfma_f32_16x16x32_bf16 v[40:43], v[132:135], v[202:205], v[40:43]
	v_mfma_f32_16x16x32_bf16 v[32:35], v[140:143], v[202:205], v[32:35]
	v_mfma_f32_16x16x32_bf16 v[24:27], v[132:135], v[210:213], v[24:27]
	v_mfma_f32_16x16x32_bf16 v[16:19], v[140:143], v[210:213], v[16:19]
	s_setprio 0
	s_setprio 1
	v_mfma_f32_16x16x32_bf16 v[44:47], v[144:147], v[176:179], v[44:47]
	v_mfma_f32_16x16x32_bf16 v[36:39], v[152:155], v[176:179], v[36:39]
	v_mfma_f32_16x16x32_bf16 v[28:31], v[144:147], v[190:193], v[28:31]
	v_mfma_f32_16x16x32_bf16 v[20:23], v[152:155], v[190:193], v[20:23]
	v_mfma_f32_16x16x32_bf16 v[12:15], v[144:147], v[198:201], v[12:15]
	v_mfma_f32_16x16x32_bf16 v[8:11], v[152:155], v[198:201], v[8:11]
	v_mfma_f32_16x16x32_bf16 v[4:7], v[144:147], v[206:209], v[4:7]
	v_mfma_f32_16x16x32_bf16 v[0:3], v[152:155], v[206:209], v[0:3]
	v_mfma_f32_16x16x32_bf16 v[44:47], v[148:151], v[180:183], v[44:47]
	v_mfma_f32_16x16x32_bf16 v[36:39], v[156:159], v[180:183], v[36:39]
	v_mfma_f32_16x16x32_bf16 v[28:31], v[148:151], v[194:197], v[28:31]
	v_mfma_f32_16x16x32_bf16 v[20:23], v[156:159], v[194:197], v[20:23]
	v_mfma_f32_16x16x32_bf16 v[12:15], v[148:151], v[202:205], v[12:15]
	v_mfma_f32_16x16x32_bf16 v[8:11], v[156:159], v[202:205], v[8:11]
	v_mfma_f32_16x16x32_bf16 v[4:7], v[148:151], v[210:213], v[4:7]
	v_mfma_f32_16x16x32_bf16 v[0:3], v[156:159], v[210:213], v[0:3]
	s_setprio 0
	s_barrier
	s_add_i32 s46, 0, 0x18000
	s_add_i32 s47, 0, 0x1c000
	v_add_u32_e32 v140, s46, v186
	v_add_u32_e32 v156, s47, v186
	ds_read_b128 v[128:131], v140
	ds_read_b128 v[132:135], v140 offset:1024
	ds_read_b128 v[136:139], v140 offset:2048
	ds_read_b128 v[140:143], v140 offset:3072
	ds_read_b128 v[144:147], v156
	ds_read_b128 v[148:151], v156 offset:1024
	ds_read_b128 v[152:155], v156 offset:2048
	ds_read_b128 v[156:159], v156 offset:3072
	s_add_u32 s44, s44, 0x100000
	s_addc_u32 s45, s45, 0
	s_mov_b32 m0, s53
	v_lshl_add_u64 v[222:223], s[44:45], 0, v[160:161]
	ds_read_b128 v[176:179], v189 offset:32768
	ds_read_b128 v[180:183], v189 offset:33792
	ds_read_b128 v[190:193], v189 offset:34816
	ds_read_b128 v[194:197], v189 offset:35840
	ds_read_b128 v[198:201], v189 offset:36864
	ds_read_b128 v[202:205], v189 offset:37888
	ds_read_b128 v[206:209], v189 offset:38912
	ds_read_b128 v[210:213], v189 offset:39936
	s_mov_b32 m0, s25
	s_nop 0
	global_load_lds_dwordx4 v[218:219], off
	s_mov_b32 m0, s39
	s_nop 0
	global_load_lds_dwordx4 v[220:221], off
	s_mov_b32 m0, s53
	s_nop 0
	global_load_lds_dwordx4 v[222:223], off
	v_lshl_add_u64 v[222:223], s[44:45], 0, v[164:165]
	s_mov_b32 m0, s54
	s_nop 0
	global_load_lds_dwordx4 v[222:223], off
	s_waitcnt vmcnt(8)
	s_waitcnt lgkmcnt(0)
	s_barrier
	s_setprio 1
	s_waitcnt lgkmcnt(0)
	v_mfma_f32_16x16x32_bf16 v[124:127], v[128:131], v[176:179], v[124:127]
	v_mfma_f32_16x16x32_bf16 v[120:123], v[136:139], v[176:179], v[120:123]
	v_mfma_f32_16x16x32_bf16 v[116:119], v[128:131], v[190:193], v[116:119]
	v_mfma_f32_16x16x32_bf16 v[112:115], v[136:139], v[190:193], v[112:115]
	v_mfma_f32_16x16x32_bf16 v[104:107], v[128:131], v[198:201], v[104:107]
	v_mfma_f32_16x16x32_bf16 v[96:99], v[136:139], v[198:201], v[96:99]
	v_mfma_f32_16x16x32_bf16 v[88:91], v[128:131], v[206:209], v[88:91]
	v_mfma_f32_16x16x32_bf16 v[80:83], v[136:139], v[206:209], v[80:83]
	v_mfma_f32_16x16x32_bf16 v[124:127], v[132:135], v[180:183], v[124:127]
	v_mfma_f32_16x16x32_bf16 v[120:123], v[140:143], v[180:183], v[120:123]
	v_mfma_f32_16x16x32_bf16 v[116:119], v[132:135], v[194:197], v[116:119]
	v_mfma_f32_16x16x32_bf16 v[112:115], v[140:143], v[194:197], v[112:115]
	v_mfma_f32_16x16x32_bf16 v[104:107], v[132:135], v[202:205], v[104:107]
	v_mfma_f32_16x16x32_bf16 v[96:99], v[140:143], v[202:205], v[96:99]
	v_mfma_f32_16x16x32_bf16 v[88:91], v[132:135], v[210:213], v[88:91]
	v_mfma_f32_16x16x32_bf16 v[80:83], v[140:143], v[210:213], v[80:83]
	s_setprio 0
	s_setprio 1
	v_mfma_f32_16x16x32_bf16 v[108:111], v[144:147], v[176:179], v[108:111]
	v_mfma_f32_16x16x32_bf16 v[100:103], v[152:155], v[176:179], v[100:103]
	v_mfma_f32_16x16x32_bf16 v[92:95], v[144:147], v[190:193], v[92:95]
	v_mfma_f32_16x16x32_bf16 v[84:87], v[152:155], v[190:193], v[84:87]
	v_mfma_f32_16x16x32_bf16 v[76:79], v[144:147], v[198:201], v[76:79]
	v_mfma_f32_16x16x32_bf16 v[72:75], v[152:155], v[198:201], v[72:75]
	v_mfma_f32_16x16x32_bf16 v[68:71], v[144:147], v[206:209], v[68:71]
	v_mfma_f32_16x16x32_bf16 v[64:67], v[152:155], v[206:209], v[64:67]
	v_mfma_f32_16x16x32_bf16 v[108:111], v[148:151], v[180:183], v[108:111]
	v_mfma_f32_16x16x32_bf16 v[100:103], v[156:159], v[180:183], v[100:103]
	v_mfma_f32_16x16x32_bf16 v[92:95], v[148:151], v[194:197], v[92:95]
	v_mfma_f32_16x16x32_bf16 v[84:87], v[156:159], v[194:197], v[84:87]
	v_mfma_f32_16x16x32_bf16 v[76:79], v[148:151], v[202:205], v[76:79]
	v_mfma_f32_16x16x32_bf16 v[72:75], v[156:159], v[202:205], v[72:75]
	v_mfma_f32_16x16x32_bf16 v[68:71], v[148:151], v[210:213], v[68:71]
	v_mfma_f32_16x16x32_bf16 v[64:67], v[156:159], v[210:213], v[64:67]
	s_setprio 0
	s_barrier
	s_add_i32 s44, s46, s52
	v_lshl_add_u64 v[214:215], v[214:215], 0, s[22:23]
	s_mov_b32 m0, s44
	ds_read_b128 v[176:179], v189 offset:49152
	ds_read_b128 v[180:183], v189 offset:50176
	ds_read_b128 v[190:193], v189 offset:51200
	ds_read_b128 v[194:197], v189 offset:52224
	ds_read_b128 v[198:201], v189 offset:53248
	ds_read_b128 v[202:205], v189 offset:54272
	ds_read_b128 v[206:209], v189 offset:55296
	ds_read_b128 v[210:213], v189 offset:56320
	global_load_lds_dwordx4 v[214:215], off
	s_add_i32 m0, s44, 0x2000
	s_add_u32 s42, s42, 0x100080
	v_lshl_add_u64 v[214:215], v[216:217], 0, s[22:23]
	s_addc_u32 s43, s43, 0
	s_add_i32 s44, s47, s52
	global_load_lds_dwordx4 v[214:215], off
	v_lshl_add_u64 v[214:215], s[42:43], 0, v[162:163]
	s_mov_b32 m0, s44
	s_nop 0
	global_load_lds_dwordx4 v[214:215], off
	v_lshl_add_u64 v[214:215], s[42:43], 0, v[166:167]
	s_add_i32 m0, s44, 0x2000
	s_nop 0
	global_load_lds_dwordx4 v[214:215], off
	v_lshl_add_u64 v[214:215], v[218:219], 0, s[22:23]
	s_mov_b32 m0, s63
	s_nop 0
	global_load_lds_dwordx4 v[214:215], off
	v_lshl_add_u64 v[214:215], v[220:221], 0, s[22:23]
	s_mov_b32 m0, s64
	s_nop 0
	global_load_lds_dwordx4 v[214:215], off
	s_waitcnt vmcnt(8)
	s_waitcnt lgkmcnt(0)
	s_barrier
	s_setprio 1
	s_waitcnt lgkmcnt(0)
	v_mfma_f32_16x16x32_bf16 v[60:63], v[128:131], v[176:179], v[60:63]
	v_mfma_f32_16x16x32_bf16 v[56:59], v[136:139], v[176:179], v[56:59]
	v_mfma_f32_16x16x32_bf16 v[52:55], v[128:131], v[190:193], v[52:55]
	v_mfma_f32_16x16x32_bf16 v[48:51], v[136:139], v[190:193], v[48:51]
	v_mfma_f32_16x16x32_bf16 v[40:43], v[128:131], v[198:201], v[40:43]
	v_mfma_f32_16x16x32_bf16 v[32:35], v[136:139], v[198:201], v[32:35]
	v_mfma_f32_16x16x32_bf16 v[24:27], v[128:131], v[206:209], v[24:27]
	v_mfma_f32_16x16x32_bf16 v[16:19], v[136:139], v[206:209], v[16:19]
	v_mfma_f32_16x16x32_bf16 v[60:63], v[132:135], v[180:183], v[60:63]
	v_mfma_f32_16x16x32_bf16 v[56:59], v[140:143], v[180:183], v[56:59]
	v_mfma_f32_16x16x32_bf16 v[52:55], v[132:135], v[194:197], v[52:55]
	v_mfma_f32_16x16x32_bf16 v[48:51], v[140:143], v[194:197], v[48:51]
	v_mfma_f32_16x16x32_bf16 v[40:43], v[132:135], v[202:205], v[40:43]
	v_mfma_f32_16x16x32_bf16 v[32:35], v[140:143], v[202:205], v[32:35]
	v_mfma_f32_16x16x32_bf16 v[24:27], v[132:135], v[210:213], v[24:27]
	v_mfma_f32_16x16x32_bf16 v[16:19], v[140:143], v[210:213], v[16:19]
	s_setprio 0
	s_setprio 1
	v_mfma_f32_16x16x32_bf16 v[44:47], v[144:147], v[176:179], v[44:47]
	v_mfma_f32_16x16x32_bf16 v[36:39], v[152:155], v[176:179], v[36:39]
	v_mfma_f32_16x16x32_bf16 v[28:31], v[144:147], v[190:193], v[28:31]
	v_mfma_f32_16x16x32_bf16 v[20:23], v[152:155], v[190:193], v[20:23]
	v_mfma_f32_16x16x32_bf16 v[12:15], v[144:147], v[198:201], v[12:15]
	v_mfma_f32_16x16x32_bf16 v[8:11], v[152:155], v[198:201], v[8:11]
	v_mfma_f32_16x16x32_bf16 v[4:7], v[144:147], v[206:209], v[4:7]
	v_mfma_f32_16x16x32_bf16 v[0:3], v[152:155], v[206:209], v[0:3]
	v_mfma_f32_16x16x32_bf16 v[44:47], v[148:151], v[180:183], v[44:47]
	v_mfma_f32_16x16x32_bf16 v[36:39], v[156:159], v[180:183], v[36:39]
	v_mfma_f32_16x16x32_bf16 v[28:31], v[148:151], v[194:197], v[28:31]
	v_mfma_f32_16x16x32_bf16 v[20:23], v[156:159], v[194:197], v[20:23]
	v_mfma_f32_16x16x32_bf16 v[12:15], v[148:151], v[202:205], v[12:15]
	v_mfma_f32_16x16x32_bf16 v[8:11], v[156:159], v[202:205], v[8:11]
	v_mfma_f32_16x16x32_bf16 v[4:7], v[148:151], v[210:213], v[4:7]
	v_mfma_f32_16x16x32_bf16 v[0:3], v[156:159], v[210:213], v[0:3]
	s_setprio 0
	s_barrier
	s_add_i32 s35, s35, 2
	s_add_u32 s40, s40, 0x100
	s_addc_u32 s41, s41, 0
	s_add_u32 s29, s29, 0x100
	s_addc_u32 s31, s31, 0
	s_cmp_gt_u32 s35, 61
	s_cbranch_scc0 .LBB0_1187
	s_and_b64 vcc, exec, s[26:27]
	s_cbranch_vccz .LBB0_1190
	s_barrier

.LBB0_1259:
	ds_read_b128 v[128:131], v179
	ds_read_b128 v[132:135], v179 offset:1024
	ds_read_b128 v[136:139], v179 offset:2048
	ds_read_b128 v[140:143], v179 offset:3072
	ds_read_b128 v[144:147], v181
	ds_read_b128 v[148:151], v181 offset:1024
	ds_read_b128 v[168:171], v181 offset:2048
	ds_read_b128 v[184:187], v181 offset:3072
	s_add_u32 s40, s38, 0xfffc0080
	s_addc_u32 s41, s39, -1
	s_cmp_eq_u32 s60, 12
	s_cselect_b32 s43, s7, s41
	s_cselect_b32 s42, s27, s40
	s_cselect_b32 s41, s29, s47
	s_cselect_b32 s40, s31, s46
	v_lshl_add_u64 v[220:221], s[38:39], 0, v[160:161]
	s_add_i32 m0, s49, 0xc000
	ds_read_b128 v[188:191], v183
	ds_read_b128 v[192:195], v183 offset:1024
	ds_read_b128 v[196:199], v183 offset:2048
	ds_read_b128 v[200:203], v183 offset:3072
	ds_read_b128 v[204:207], v183 offset:4096
	ds_read_b128 v[208:211], v183 offset:5120
	ds_read_b128 v[212:215], v183 offset:6144
	ds_read_b128 v[216:219], v183 offset:7168
	global_load_lds_dwordx4 v[220:221], off
	v_lshl_add_u64 v[220:221], s[38:39], 0, v[162:163]
	s_add_i32 m0, s49, 0xe000
	s_nop 0
	global_load_lds_dwordx4 v[220:221], off
	s_waitcnt vmcnt(8)
	s_waitcnt lgkmcnt(0)
	s_barrier
	s_setprio 1
	s_waitcnt lgkmcnt(0)
	v_mfma_f32_16x16x32_bf16 v[124:127], v[128:131], v[188:191], v[124:127]
	v_mfma_f32_16x16x32_bf16 v[120:123], v[136:139], v[188:191], v[120:123]
	v_mfma_f32_16x16x32_bf16 v[108:111], v[128:131], v[196:199], v[108:111]
	v_mfma_f32_16x16x32_bf16 v[104:107], v[136:139], v[196:199], v[104:107]
	v_mfma_f32_16x16x32_bf16 v[92:95], v[128:131], v[204:207], v[92:95]
	v_mfma_f32_16x16x32_bf16 v[88:91], v[136:139], v[204:207], v[88:91]
	v_mfma_f32_16x16x32_bf16 v[76:79], v[128:131], v[212:215], v[76:79]
	v_mfma_f32_16x16x32_bf16 v[72:75], v[136:139], v[212:215], v[72:75]
	v_mfma_f32_16x16x32_bf16 v[124:127], v[132:135], v[192:195], v[124:127]
	v_mfma_f32_16x16x32_bf16 v[120:123], v[140:143], v[192:195], v[120:123]
	v_mfma_f32_16x16x32_bf16 v[108:111], v[132:135], v[200:203], v[108:111]
	v_mfma_f32_16x16x32_bf16 v[104:107], v[140:143], v[200:203], v[104:107]
	v_mfma_f32_16x16x32_bf16 v[92:95], v[132:135], v[208:211], v[92:95]
	v_mfma_f32_16x16x32_bf16 v[88:91], v[140:143], v[208:211], v[88:91]
	v_mfma_f32_16x16x32_bf16 v[76:79], v[132:135], v[216:219], v[76:79]
	v_mfma_f32_16x16x32_bf16 v[72:75], v[140:143], v[216:219], v[72:75]
	s_setprio 0
	s_setprio 1
	v_mfma_f32_16x16x32_bf16 v[116:119], v[144:147], v[188:191], v[116:119]
	v_mfma_f32_16x16x32_bf16 v[112:115], v[168:171], v[188:191], v[112:115]
	v_mfma_f32_16x16x32_bf16 v[100:103], v[144:147], v[196:199], v[100:103]
	v_mfma_f32_16x16x32_bf16 v[96:99], v[168:171], v[196:199], v[96:99]
	v_mfma_f32_16x16x32_bf16 v[84:87], v[144:147], v[204:207], v[84:87]
	v_mfma_f32_16x16x32_bf16 v[80:83], v[168:171], v[204:207], v[80:83]
	v_mfma_f32_16x16x32_bf16 v[68:71], v[144:147], v[212:215], v[68:71]
	v_mfma_f32_16x16x32_bf16 v[64:67], v[168:171], v[212:215], v[64:67]
	v_mfma_f32_16x16x32_bf16 v[116:119], v[148:151], v[192:195], v[116:119]
	v_mfma_f32_16x16x32_bf16 v[112:115], v[184:187], v[192:195], v[112:115]
	v_mfma_f32_16x16x32_bf16 v[100:103], v[148:151], v[200:203], v[100:103]
	v_mfma_f32_16x16x32_bf16 v[96:99], v[184:187], v[200:203], v[96:99]
	v_mfma_f32_16x16x32_bf16 v[84:87], v[148:151], v[208:211], v[84:87]
	v_mfma_f32_16x16x32_bf16 v[80:83], v[184:187], v[208:211], v[80:83]
	v_mfma_f32_16x16x32_bf16 v[68:71], v[148:151], v[216:219], v[68:71]
	v_mfma_f32_16x16x32_bf16 v[64:67], v[184:187], v[216:219], v[64:67]
	s_setprio 0
	s_barrier
	s_add_i32 s61, s67, s48
	v_lshl_add_u64 v[220:221], s[40:41], 0, v[156:157]
	s_mov_b32 m0, s61
	ds_read_b128 v[188:191], v183 offset:16384
	ds_read_b128 v[192:195], v183 offset:17408
	ds_read_b128 v[196:199], v183 offset:18432
	ds_read_b128 v[200:203], v183 offset:19456
	ds_read_b128 v[204:207], v183 offset:20480
	ds_read_b128 v[208:211], v183 offset:21504
	ds_read_b128 v[212:215], v183 offset:22528
	ds_read_b128 v[216:219], v183 offset:23552
	global_load_lds_dwordx4 v[220:221], off
	s_add_i32 m0, s61, 0x2000
	s_add_u32 s72, s40, 0x40000
	v_lshl_add_u64 v[222:223], s[40:41], 0, v[152:153]
	s_addc_u32 s73, s41, 0
	s_add_i32 s61, s68, s48
	global_load_lds_dwordx4 v[222:223], off
	v_lshl_add_u64 v[224:225], s[72:73], 0, v[156:157]
	s_mov_b32 m0, s61
	v_lshl_add_u64 v[226:227], s[42:43], 0, v[154:155]
	global_load_lds_dwordx4 v[224:225], off
	v_lshl_add_u64 v[224:225], s[72:73], 0, v[152:153]
	s_add_i32 m0, s61, 0x2000
	s_nop 0
	global_load_lds_dwordx4 v[224:225], off
	v_lshl_add_u64 v[224:225], s[42:43], 0, v[158:159]
	s_waitcnt vmcnt(6)
	s_waitcnt lgkmcnt(0)
	s_barrier
	s_setprio 1
	s_waitcnt lgkmcnt(0)
	v_mfma_f32_16x16x32_bf16 v[60:63], v[128:131], v[188:191], v[60:63]
	v_mfma_f32_16x16x32_bf16 v[56:59], v[136:139], v[188:191], v[56:59]
	v_mfma_f32_16x16x32_bf16 v[44:47], v[128:131], v[196:199], v[44:47]
	v_mfma_f32_16x16x32_bf16 v[40:43], v[136:139], v[196:199], v[40:43]
	v_mfma_f32_16x16x32_bf16 v[28:31], v[128:131], v[204:207], v[28:31]
	v_mfma_f32_16x16x32_bf16 v[24:27], v[136:139], v[204:207], v[24:27]
	v_mfma_f32_16x16x32_bf16 v[12:15], v[128:131], v[212:215], v[12:15]
	v_mfma_f32_16x16x32_bf16 v[8:11], v[136:139], v[212:215], v[8:11]
	v_mfma_f32_16x16x32_bf16 v[60:63], v[132:135], v[192:195], v[60:63]
	v_mfma_f32_16x16x32_bf16 v[56:59], v[140:143], v[192:195], v[56:59]
	v_mfma_f32_16x16x32_bf16 v[44:47], v[132:135], v[200:203], v[44:47]
	v_mfma_f32_16x16x32_bf16 v[40:43], v[140:143], v[200:203], v[40:43]
	v_mfma_f32_16x16x32_bf16 v[28:31], v[132:135], v[208:211], v[28:31]
	v_mfma_f32_16x16x32_bf16 v[24:27], v[140:143], v[208:211], v[24:27]
	v_mfma_f32_16x16x32_bf16 v[12:15], v[132:135], v[216:219], v[12:15]
	v_mfma_f32_16x16x32_bf16 v[8:11], v[140:143], v[216:219], v[8:11]
	s_setprio 0
	s_setprio 1
	v_mfma_f32_16x16x32_bf16 v[52:55], v[144:147], v[188:191], v[52:55]
	v_mfma_f32_16x16x32_bf16 v[48:51], v[168:171], v[188:191], v[48:51]
	v_mfma_f32_16x16x32_bf16 v[36:39], v[144:147], v[196:199], v[36:39]
	v_mfma_f32_16x16x32_bf16 v[32:35], v[168:171], v[196:199], v[32:35]
	v_mfma_f32_16x16x32_bf16 v[20:23], v[144:147], v[204:207], v[20:23]
	v_mfma_f32_16x16x32_bf16 v[16:19], v[168:171], v[204:207], v[16:19]
	v_mfma_f32_16x16x32_bf16 v[4:7], v[144:147], v[212:215], v[4:7]
	v_mfma_f32_16x16x32_bf16 v[0:3], v[168:171], v[212:215], v[0:3]
	v_mfma_f32_16x16x32_bf16 v[52:55], v[148:151], v[192:195], v[52:55]
	v_mfma_f32_16x16x32_bf16 v[48:51], v[184:187], v[192:195], v[48:51]
	v_mfma_f32_16x16x32_bf16 v[36:39], v[148:151], v[200:203], v[36:39]
	v_mfma_f32_16x16x32_bf16 v[32:35], v[184:187], v[200:203], v[32:35]
	v_mfma_f32_16x16x32_bf16 v[20:23], v[148:151], v[208:211], v[20:23]
	v_mfma_f32_16x16x32_bf16 v[16:19], v[184:187], v[208:211], v[16:19]
	v_mfma_f32_16x16x32_bf16 v[4:7], v[148:151], v[216:219], v[4:7]
	v_mfma_f32_16x16x32_bf16 v[0:3], v[184:187], v[216:219], v[0:3]
	s_setprio 0
	s_barrier
	s_add_i32 s61, 0, 0x18000
	s_add_i32 s71, 0, 0x1c000
	v_add_u32_e32 v140, s61, v177
	v_add_u32_e32 v172, s71, v177
	ds_read_b128 v[128:131], v140
	ds_read_b128 v[132:135], v140 offset:1024
	ds_read_b128 v[136:139], v140 offset:2048
	ds_read_b128 v[140:143], v140 offset:3072
	ds_read_b128 v[144:147], v172
	ds_read_b128 v[148:151], v172 offset:1024
	ds_read_b128 v[168:171], v172 offset:2048
	ds_read_b128 v[184:187], v172 offset:3072
	s_add_u32 s42, s42, 0x40000
	s_addc_u32 s43, s43, 0
	s_mov_b32 m0, s51
	v_lshl_add_u64 v[228:229], s[42:43], 0, v[158:159]
	ds_read_b128 v[188:191], v183 offset:32768
	ds_read_b128 v[192:195], v183 offset:33792
	ds_read_b128 v[196:199], v183 offset:34816
	ds_read_b128 v[200:203], v183 offset:35840
	ds_read_b128 v[204:207], v183 offset:36864
	ds_read_b128 v[208:211], v183 offset:37888
	ds_read_b128 v[212:215], v183 offset:38912
	ds_read_b128 v[216:219], v183 offset:39936
	s_mov_b32 m0, s49
	s_nop 0
	global_load_lds_dwordx4 v[224:225], off
	s_mov_b32 m0, s50
	s_nop 0
	global_load_lds_dwordx4 v[226:227], off
	s_mov_b32 m0, s51
	s_nop 0
	global_load_lds_dwordx4 v[228:229], off
	v_lshl_add_u64 v[228:229], s[42:43], 0, v[154:155]
	s_mov_b32 m0, s52
	s_nop 0
	global_load_lds_dwordx4 v[228:229], off
	s_waitcnt vmcnt(8)
	s_waitcnt lgkmcnt(0)
	s_barrier
	s_setprio 1
	s_waitcnt lgkmcnt(0)
	v_mfma_f32_16x16x32_bf16 v[124:127], v[128:131], v[188:191], v[124:127]
	v_mfma_f32_16x16x32_bf16 v[120:123], v[136:139], v[188:191], v[120:123]
	v_mfma_f32_16x16x32_bf16 v[108:111], v[128:131], v[196:199], v[108:111]
	v_mfma_f32_16x16x32_bf16 v[104:107], v[136:139], v[196:199], v[104:107]
	v_mfma_f32_16x16x32_bf16 v[92:95], v[128:131], v[204:207], v[92:95]
	v_mfma_f32_16x16x32_bf16 v[88:91], v[136:139], v[204:207], v[88:91]
	v_mfma_f32_16x16x32_bf16 v[76:79], v[128:131], v[212:215], v[76:79]
	v_mfma_f32_16x16x32_bf16 v[72:75], v[136:139], v[212:215], v[72:75]
	v_mfma_f32_16x16x32_bf16 v[124:127], v[132:135], v[192:195], v[124:127]
	v_mfma_f32_16x16x32_bf16 v[120:123], v[140:143], v[192:195], v[120:123]
	v_mfma_f32_16x16x32_bf16 v[108:111], v[132:135], v[200:203], v[108:111]
	v_mfma_f32_16x16x32_bf16 v[104:107], v[140:143], v[200:203], v[104:107]
	v_mfma_f32_16x16x32_bf16 v[92:95], v[132:135], v[208:211], v[92:95]
	v_mfma_f32_16x16x32_bf16 v[88:91], v[140:143], v[208:211], v[88:91]
	v_mfma_f32_16x16x32_bf16 v[76:79], v[132:135], v[216:219], v[76:79]
	v_mfma_f32_16x16x32_bf16 v[72:75], v[140:143], v[216:219], v[72:75]
	s_setprio 0
	s_setprio 1
	v_mfma_f32_16x16x32_bf16 v[116:119], v[144:147], v[188:191], v[116:119]
	v_mfma_f32_16x16x32_bf16 v[112:115], v[168:171], v[188:191], v[112:115]
	v_mfma_f32_16x16x32_bf16 v[100:103], v[144:147], v[196:199], v[100:103]
	v_mfma_f32_16x16x32_bf16 v[96:99], v[168:171], v[196:199], v[96:99]
	v_mfma_f32_16x16x32_bf16 v[84:87], v[144:147], v[204:207], v[84:87]
	v_mfma_f32_16x16x32_bf16 v[80:83], v[168:171], v[204:207], v[80:83]
	v_mfma_f32_16x16x32_bf16 v[68:71], v[144:147], v[212:215], v[68:71]
	v_mfma_f32_16x16x32_bf16 v[64:67], v[168:171], v[212:215], v[64:67]
	v_mfma_f32_16x16x32_bf16 v[116:119], v[148:151], v[192:195], v[116:119]
	v_mfma_f32_16x16x32_bf16 v[112:115], v[184:187], v[192:195], v[112:115]
	v_mfma_f32_16x16x32_bf16 v[100:103], v[148:151], v[200:203], v[100:103]
	v_mfma_f32_16x16x32_bf16 v[96:99], v[184:187], v[200:203], v[96:99]
	v_mfma_f32_16x16x32_bf16 v[84:87], v[148:151], v[208:211], v[84:87]
	v_mfma_f32_16x16x32_bf16 v[80:83], v[184:187], v[208:211], v[80:83]
	v_mfma_f32_16x16x32_bf16 v[68:71], v[148:151], v[216:219], v[68:71]
	v_mfma_f32_16x16x32_bf16 v[64:67], v[184:187], v[216:219], v[64:67]
	s_setprio 0
	s_barrier
	s_add_i32 s42, s61, s48
	v_lshl_add_u64 v[220:221], v[220:221], 0, s[18:19]
	s_mov_b32 m0, s42
	ds_read_b128 v[188:191], v183 offset:49152
	ds_read_b128 v[192:195], v183 offset:50176
	ds_read_b128 v[196:199], v183 offset:51200
	ds_read_b128 v[200:203], v183 offset:52224
	ds_read_b128 v[204:207], v183 offset:53248
	ds_read_b128 v[208:211], v183 offset:54272
	ds_read_b128 v[212:215], v183 offset:55296
	ds_read_b128 v[216:219], v183 offset:56320
	global_load_lds_dwordx4 v[220:221], off
	s_add_i32 m0, s42, 0x2000
	s_add_u32 s40, s40, 0x40080
	v_lshl_add_u64 v[220:221], v[222:223], 0, s[18:19]
	s_addc_u32 s41, s41, 0
	s_add_i32 s42, s71, s48
	global_load_lds_dwordx4 v[220:221], off
	v_lshl_add_u64 v[220:221], s[40:41], 0, v[156:157]
	s_mov_b32 m0, s42
	s_nop 0
	global_load_lds_dwordx4 v[220:221], off
	v_lshl_add_u64 v[220:221], s[40:41], 0, v[152:153]
	s_add_i32 m0, s42, 0x2000
	s_nop 0
	global_load_lds_dwordx4 v[220:221], off
	v_lshl_add_u64 v[220:221], v[224:225], 0, s[18:19]
	s_mov_b32 m0, s63
	s_nop 0
	global_load_lds_dwordx4 v[220:221], off
	v_lshl_add_u64 v[220:221], v[226:227], 0, s[18:19]
	s_mov_b32 m0, s64
	s_nop 0
	global_load_lds_dwordx4 v[220:221], off
	s_waitcnt vmcnt(8)
	s_waitcnt lgkmcnt(0)
	s_barrier
	s_setprio 1
	s_waitcnt lgkmcnt(0)
	v_mfma_f32_16x16x32_bf16 v[60:63], v[128:131], v[188:191], v[60:63]
	v_mfma_f32_16x16x32_bf16 v[56:59], v[136:139], v[188:191], v[56:59]
	v_mfma_f32_16x16x32_bf16 v[44:47], v[128:131], v[196:199], v[44:47]
	v_mfma_f32_16x16x32_bf16 v[40:43], v[136:139], v[196:199], v[40:43]
	v_mfma_f32_16x16x32_bf16 v[28:31], v[128:131], v[204:207], v[28:31]
	v_mfma_f32_16x16x32_bf16 v[24:27], v[136:139], v[204:207], v[24:27]
	v_mfma_f32_16x16x32_bf16 v[12:15], v[128:131], v[212:215], v[12:15]
	v_mfma_f32_16x16x32_bf16 v[8:11], v[136:139], v[212:215], v[8:11]
	v_mfma_f32_16x16x32_bf16 v[60:63], v[132:135], v[192:195], v[60:63]
	v_mfma_f32_16x16x32_bf16 v[56:59], v[140:143], v[192:195], v[56:59]
	v_mfma_f32_16x16x32_bf16 v[44:47], v[132:135], v[200:203], v[44:47]
	v_mfma_f32_16x16x32_bf16 v[40:43], v[140:143], v[200:203], v[40:43]
	v_mfma_f32_16x16x32_bf16 v[28:31], v[132:135], v[208:211], v[28:31]
	v_mfma_f32_16x16x32_bf16 v[24:27], v[140:143], v[208:211], v[24:27]
	v_mfma_f32_16x16x32_bf16 v[12:15], v[132:135], v[216:219], v[12:15]
	v_mfma_f32_16x16x32_bf16 v[8:11], v[140:143], v[216:219], v[8:11]
	s_setprio 0
	s_setprio 1
	v_mfma_f32_16x16x32_bf16 v[52:55], v[144:147], v[188:191], v[52:55]
	v_mfma_f32_16x16x32_bf16 v[48:51], v[168:171], v[188:191], v[48:51]
	v_mfma_f32_16x16x32_bf16 v[36:39], v[144:147], v[196:199], v[36:39]
	v_mfma_f32_16x16x32_bf16 v[32:35], v[168:171], v[196:199], v[32:35]
	v_mfma_f32_16x16x32_bf16 v[20:23], v[144:147], v[204:207], v[20:23]
	v_mfma_f32_16x16x32_bf16 v[16:19], v[168:171], v[204:207], v[16:19]
	v_mfma_f32_16x16x32_bf16 v[4:7], v[144:147], v[212:215], v[4:7]
	v_mfma_f32_16x16x32_bf16 v[0:3], v[168:171], v[212:215], v[0:3]
	v_mfma_f32_16x16x32_bf16 v[52:55], v[148:151], v[192:195], v[52:55]
	v_mfma_f32_16x16x32_bf16 v[48:51], v[184:187], v[192:195], v[48:51]
	v_mfma_f32_16x16x32_bf16 v[36:39], v[148:151], v[200:203], v[36:39]
	v_mfma_f32_16x16x32_bf16 v[32:35], v[184:187], v[200:203], v[32:35]
	v_mfma_f32_16x16x32_bf16 v[20:23], v[148:151], v[208:211], v[20:23]
	v_mfma_f32_16x16x32_bf16 v[16:19], v[184:187], v[208:211], v[16:19]
	v_mfma_f32_16x16x32_bf16 v[4:7], v[148:151], v[216:219], v[4:7]
	v_mfma_f32_16x16x32_bf16 v[0:3], v[184:187], v[216:219], v[0:3]
	s_setprio 0
	s_barrier
	s_add_i32 s60, s60, 2
	s_add_u32 s38, s38, 0x100
	s_addc_u32 s39, s39, 0
	s_add_u32 s46, s46, 0x100
	s_addc_u32 s47, s47, 0
	s_cmp_gt_u32 s60, 13
	s_cbranch_scc0 .LBB0_1259
	s_and_b64 vcc, exec, s[20:21]
	s_cbranch_vccz .LBB0_1262
	s_barrier

.LBB0_1340:
	ds_read_b128 v[128:131], v187
	ds_read_b128 v[132:135], v187 offset:1024
	ds_read_b128 v[136:139], v187 offset:2048
	ds_read_b128 v[140:143], v187 offset:3072
	ds_read_b128 v[144:147], v188
	ds_read_b128 v[148:151], v188 offset:1024
	ds_read_b128 v[152:155], v188 offset:2048
	ds_read_b128 v[156:159], v188 offset:3072
	s_add_u32 s40, s38, 0xfff00080
	s_addc_u32 s41, s39, -1
	s_cmp_eq_u32 s31, 28
	s_cselect_b32 s43, s7, s41
	s_cselect_b32 s42, s6, s40
	s_cselect_b32 s41, s35, s29
	s_cselect_b32 s40, s34, s27
	v_lshl_add_u64 v[214:215], s[38:39], 0, v[168:169]
	s_add_i32 m0, s23, 0xc000
	ds_read_b128 v[176:179], v189
	ds_read_b128 v[180:183], v189 offset:1024
	ds_read_b128 v[190:193], v189 offset:2048
	ds_read_b128 v[194:197], v189 offset:3072
	ds_read_b128 v[198:201], v189 offset:4096
	ds_read_b128 v[202:205], v189 offset:5120
	ds_read_b128 v[206:209], v189 offset:6144
	ds_read_b128 v[210:213], v189 offset:7168
	global_load_lds_dwordx4 v[214:215], off
	v_lshl_add_u64 v[214:215], s[38:39], 0, v[170:171]
	s_add_i32 m0, s23, 0xe000
	s_nop 0
	global_load_lds_dwordx4 v[214:215], off
	s_waitcnt vmcnt(8)
	s_waitcnt lgkmcnt(0)
	s_barrier
	s_setprio 1
	s_waitcnt lgkmcnt(0)
	v_mfma_f32_16x16x32_bf16 v[124:127], v[128:131], v[176:179], v[124:127]
	v_mfma_f32_16x16x32_bf16 v[120:123], v[136:139], v[176:179], v[120:123]
	v_mfma_f32_16x16x32_bf16 v[116:119], v[128:131], v[190:193], v[116:119]
	v_mfma_f32_16x16x32_bf16 v[112:115], v[136:139], v[190:193], v[112:115]
	v_mfma_f32_16x16x32_bf16 v[104:107], v[128:131], v[198:201], v[104:107]
	v_mfma_f32_16x16x32_bf16 v[96:99], v[136:139], v[198:201], v[96:99]
	v_mfma_f32_16x16x32_bf16 v[88:91], v[128:131], v[206:209], v[88:91]
	v_mfma_f32_16x16x32_bf16 v[80:83], v[136:139], v[206:209], v[80:83]
	v_mfma_f32_16x16x32_bf16 v[124:127], v[132:135], v[180:183], v[124:127]
	v_mfma_f32_16x16x32_bf16 v[120:123], v[140:143], v[180:183], v[120:123]
	v_mfma_f32_16x16x32_bf16 v[116:119], v[132:135], v[194:197], v[116:119]
	v_mfma_f32_16x16x32_bf16 v[112:115], v[140:143], v[194:197], v[112:115]
	v_mfma_f32_16x16x32_bf16 v[104:107], v[132:135], v[202:205], v[104:107]
	v_mfma_f32_16x16x32_bf16 v[96:99], v[140:143], v[202:205], v[96:99]
	v_mfma_f32_16x16x32_bf16 v[88:91], v[132:135], v[210:213], v[88:91]
	v_mfma_f32_16x16x32_bf16 v[80:83], v[140:143], v[210:213], v[80:83]
	s_setprio 0
	s_setprio 1
	v_mfma_f32_16x16x32_bf16 v[108:111], v[144:147], v[176:179], v[108:111]
	v_mfma_f32_16x16x32_bf16 v[100:103], v[152:155], v[176:179], v[100:103]
	v_mfma_f32_16x16x32_bf16 v[92:95], v[144:147], v[190:193], v[92:95]
	v_mfma_f32_16x16x32_bf16 v[84:87], v[152:155], v[190:193], v[84:87]
	v_mfma_f32_16x16x32_bf16 v[76:79], v[144:147], v[198:201], v[76:79]
	v_mfma_f32_16x16x32_bf16 v[72:75], v[152:155], v[198:201], v[72:75]
	v_mfma_f32_16x16x32_bf16 v[68:71], v[144:147], v[206:209], v[68:71]
	v_mfma_f32_16x16x32_bf16 v[64:67], v[152:155], v[206:209], v[64:67]
	v_mfma_f32_16x16x32_bf16 v[108:111], v[148:151], v[180:183], v[108:111]
	v_mfma_f32_16x16x32_bf16 v[100:103], v[156:159], v[180:183], v[100:103]
	v_mfma_f32_16x16x32_bf16 v[92:95], v[148:151], v[194:197], v[92:95]
	v_mfma_f32_16x16x32_bf16 v[84:87], v[156:159], v[194:197], v[84:87]
	v_mfma_f32_16x16x32_bf16 v[76:79], v[148:151], v[202:205], v[76:79]
	v_mfma_f32_16x16x32_bf16 v[72:75], v[156:159], v[202:205], v[72:75]
	v_mfma_f32_16x16x32_bf16 v[68:71], v[148:151], v[210:213], v[68:71]
	v_mfma_f32_16x16x32_bf16 v[64:67], v[156:159], v[210:213], v[64:67]
	s_setprio 0
	s_barrier
	s_add_i32 s46, s65, s50
	v_lshl_add_u64 v[214:215], s[40:41], 0, v[162:163]
	s_mov_b32 m0, s46
	ds_read_b128 v[176:179], v189 offset:16384
	ds_read_b128 v[180:183], v189 offset:17408
	ds_read_b128 v[190:193], v189 offset:18432
	ds_read_b128 v[194:197], v189 offset:19456
	ds_read_b128 v[198:201], v189 offset:20480
	ds_read_b128 v[202:205], v189 offset:21504
	ds_read_b128 v[206:209], v189 offset:22528
	ds_read_b128 v[210:213], v189 offset:23552
	global_load_lds_dwordx4 v[214:215], off
	s_add_i32 m0, s46, 0x2000
	s_add_u32 s46, s40, 0x100000
	v_lshl_add_u64 v[216:217], s[40:41], 0, v[166:167]
	s_addc_u32 s47, s41, 0
	s_add_i32 s60, s66, s50
	global_load_lds_dwordx4 v[216:217], off
	v_lshl_add_u64 v[218:219], s[46:47], 0, v[162:163]
	s_mov_b32 m0, s60
	v_lshl_add_u64 v[220:221], s[42:43], 0, v[164:165]
	global_load_lds_dwordx4 v[218:219], off
	v_lshl_add_u64 v[218:219], s[46:47], 0, v[166:167]
	s_add_i32 m0, s60, 0x2000
	s_nop 0
	global_load_lds_dwordx4 v[218:219], off
	v_lshl_add_u64 v[218:219], s[42:43], 0, v[160:161]
	s_waitcnt vmcnt(6)
	s_waitcnt lgkmcnt(0)
	s_barrier
	s_setprio 1
	s_waitcnt lgkmcnt(0)
	v_mfma_f32_16x16x32_bf16 v[60:63], v[128:131], v[176:179], v[60:63]
	v_mfma_f32_16x16x32_bf16 v[56:59], v[136:139], v[176:179], v[56:59]
	v_mfma_f32_16x16x32_bf16 v[52:55], v[128:131], v[190:193], v[52:55]
	v_mfma_f32_16x16x32_bf16 v[48:51], v[136:139], v[190:193], v[48:51]
	v_mfma_f32_16x16x32_bf16 v[40:43], v[128:131], v[198:201], v[40:43]
	v_mfma_f32_16x16x32_bf16 v[32:35], v[136:139], v[198:201], v[32:35]
	v_mfma_f32_16x16x32_bf16 v[24:27], v[128:131], v[206:209], v[24:27]
	v_mfma_f32_16x16x32_bf16 v[16:19], v[136:139], v[206:209], v[16:19]
	v_mfma_f32_16x16x32_bf16 v[60:63], v[132:135], v[180:183], v[60:63]
	v_mfma_f32_16x16x32_bf16 v[56:59], v[140:143], v[180:183], v[56:59]
	v_mfma_f32_16x16x32_bf16 v[52:55], v[132:135], v[194:197], v[52:55]
	v_mfma_f32_16x16x32_bf16 v[48:51], v[140:143], v[194:197], v[48:51]
	v_mfma_f32_16x16x32_bf16 v[40:43], v[132:135], v[202:205], v[40:43]
	v_mfma_f32_16x16x32_bf16 v[32:35], v[140:143], v[202:205], v[32:35]
	v_mfma_f32_16x16x32_bf16 v[24:27], v[132:135], v[210:213], v[24:27]
	v_mfma_f32_16x16x32_bf16 v[16:19], v[140:143], v[210:213], v[16:19]
	s_setprio 0
	s_setprio 1
	v_mfma_f32_16x16x32_bf16 v[44:47], v[144:147], v[176:179], v[44:47]
	v_mfma_f32_16x16x32_bf16 v[36:39], v[152:155], v[176:179], v[36:39]
	v_mfma_f32_16x16x32_bf16 v[28:31], v[144:147], v[190:193], v[28:31]
	v_mfma_f32_16x16x32_bf16 v[20:23], v[152:155], v[190:193], v[20:23]
	v_mfma_f32_16x16x32_bf16 v[12:15], v[144:147], v[198:201], v[12:15]
	v_mfma_f32_16x16x32_bf16 v[8:11], v[152:155], v[198:201], v[8:11]
	v_mfma_f32_16x16x32_bf16 v[4:7], v[144:147], v[206:209], v[4:7]
	v_mfma_f32_16x16x32_bf16 v[0:3], v[152:155], v[206:209], v[0:3]
	v_mfma_f32_16x16x32_bf16 v[44:47], v[148:151], v[180:183], v[44:47]
	v_mfma_f32_16x16x32_bf16 v[36:39], v[156:159], v[180:183], v[36:39]
	v_mfma_f32_16x16x32_bf16 v[28:31], v[148:151], v[194:197], v[28:31]
	v_mfma_f32_16x16x32_bf16 v[20:23], v[156:159], v[194:197], v[20:23]
	v_mfma_f32_16x16x32_bf16 v[12:15], v[148:151], v[202:205], v[12:15]
	v_mfma_f32_16x16x32_bf16 v[8:11], v[156:159], v[202:205], v[8:11]
	v_mfma_f32_16x16x32_bf16 v[4:7], v[148:151], v[210:213], v[4:7]
	v_mfma_f32_16x16x32_bf16 v[0:3], v[156:159], v[210:213], v[0:3]
	s_setprio 0
	s_barrier
	s_add_i32 s46, 0, 0x18000
	s_add_i32 s47, 0, 0x1c000
	v_add_u32_e32 v140, s46, v186
	v_add_u32_e32 v156, s47, v186
	ds_read_b128 v[128:131], v140
	ds_read_b128 v[132:135], v140 offset:1024
	ds_read_b128 v[136:139], v140 offset:2048
	ds_read_b128 v[140:143], v140 offset:3072
	ds_read_b128 v[144:147], v156
	ds_read_b128 v[148:151], v156 offset:1024
	ds_read_b128 v[152:155], v156 offset:2048
	ds_read_b128 v[156:159], v156 offset:3072
	s_add_u32 s42, s42, 0x100000
	s_addc_u32 s43, s43, 0
	s_mov_b32 m0, s51
	v_lshl_add_u64 v[222:223], s[42:43], 0, v[160:161]
	ds_read_b128 v[176:179], v189 offset:32768
	ds_read_b128 v[180:183], v189 offset:33792
	ds_read_b128 v[190:193], v189 offset:34816
	ds_read_b128 v[194:197], v189 offset:35840
	ds_read_b128 v[198:201], v189 offset:36864
	ds_read_b128 v[202:205], v189 offset:37888
	ds_read_b128 v[206:209], v189 offset:38912
	ds_read_b128 v[210:213], v189 offset:39936
	s_mov_b32 m0, s23
	s_nop 0
	global_load_lds_dwordx4 v[218:219], off
	s_mov_b32 m0, s37
	s_nop 0
	global_load_lds_dwordx4 v[220:221], off
	s_mov_b32 m0, s51
	s_nop 0
	global_load_lds_dwordx4 v[222:223], off
	v_lshl_add_u64 v[222:223], s[42:43], 0, v[164:165]
	s_mov_b32 m0, s52
	s_nop 0
	global_load_lds_dwordx4 v[222:223], off
	s_waitcnt vmcnt(8)
	s_waitcnt lgkmcnt(0)
	s_barrier
	s_setprio 1
	s_waitcnt lgkmcnt(0)
	v_mfma_f32_16x16x32_bf16 v[124:127], v[128:131], v[176:179], v[124:127]
	v_mfma_f32_16x16x32_bf16 v[120:123], v[136:139], v[176:179], v[120:123]
	v_mfma_f32_16x16x32_bf16 v[116:119], v[128:131], v[190:193], v[116:119]
	v_mfma_f32_16x16x32_bf16 v[112:115], v[136:139], v[190:193], v[112:115]
	v_mfma_f32_16x16x32_bf16 v[104:107], v[128:131], v[198:201], v[104:107]
	v_mfma_f32_16x16x32_bf16 v[96:99], v[136:139], v[198:201], v[96:99]
	v_mfma_f32_16x16x32_bf16 v[88:91], v[128:131], v[206:209], v[88:91]
	v_mfma_f32_16x16x32_bf16 v[80:83], v[136:139], v[206:209], v[80:83]
	v_mfma_f32_16x16x32_bf16 v[124:127], v[132:135], v[180:183], v[124:127]
	v_mfma_f32_16x16x32_bf16 v[120:123], v[140:143], v[180:183], v[120:123]
	v_mfma_f32_16x16x32_bf16 v[116:119], v[132:135], v[194:197], v[116:119]
	v_mfma_f32_16x16x32_bf16 v[112:115], v[140:143], v[194:197], v[112:115]
	v_mfma_f32_16x16x32_bf16 v[104:107], v[132:135], v[202:205], v[104:107]
	v_mfma_f32_16x16x32_bf16 v[96:99], v[140:143], v[202:205], v[96:99]
	v_mfma_f32_16x16x32_bf16 v[88:91], v[132:135], v[210:213], v[88:91]
	v_mfma_f32_16x16x32_bf16 v[80:83], v[140:143], v[210:213], v[80:83]
	s_setprio 0
	s_setprio 1
	v_mfma_f32_16x16x32_bf16 v[108:111], v[144:147], v[176:179], v[108:111]
	v_mfma_f32_16x16x32_bf16 v[100:103], v[152:155], v[176:179], v[100:103]
	v_mfma_f32_16x16x32_bf16 v[92:95], v[144:147], v[190:193], v[92:95]
	v_mfma_f32_16x16x32_bf16 v[84:87], v[152:155], v[190:193], v[84:87]
	v_mfma_f32_16x16x32_bf16 v[76:79], v[144:147], v[198:201], v[76:79]
	v_mfma_f32_16x16x32_bf16 v[72:75], v[152:155], v[198:201], v[72:75]
	v_mfma_f32_16x16x32_bf16 v[68:71], v[144:147], v[206:209], v[68:71]
	v_mfma_f32_16x16x32_bf16 v[64:67], v[152:155], v[206:209], v[64:67]
	v_mfma_f32_16x16x32_bf16 v[108:111], v[148:151], v[180:183], v[108:111]
	v_mfma_f32_16x16x32_bf16 v[100:103], v[156:159], v[180:183], v[100:103]
	v_mfma_f32_16x16x32_bf16 v[92:95], v[148:151], v[194:197], v[92:95]
	v_mfma_f32_16x16x32_bf16 v[84:87], v[156:159], v[194:197], v[84:87]
	v_mfma_f32_16x16x32_bf16 v[76:79], v[148:151], v[202:205], v[76:79]
	v_mfma_f32_16x16x32_bf16 v[72:75], v[156:159], v[202:205], v[72:75]
	v_mfma_f32_16x16x32_bf16 v[68:71], v[148:151], v[210:213], v[68:71]
	v_mfma_f32_16x16x32_bf16 v[64:67], v[156:159], v[210:213], v[64:67]
	s_setprio 0
	s_barrier
	s_add_i32 s42, s46, s50
	v_lshl_add_u64 v[214:215], v[214:215], 0, s[20:21]
	s_mov_b32 m0, s42
	ds_read_b128 v[176:179], v189 offset:49152
	ds_read_b128 v[180:183], v189 offset:50176
	ds_read_b128 v[190:193], v189 offset:51200
	ds_read_b128 v[194:197], v189 offset:52224
	ds_read_b128 v[198:201], v189 offset:53248
	ds_read_b128 v[202:205], v189 offset:54272
	ds_read_b128 v[206:209], v189 offset:55296
	ds_read_b128 v[210:213], v189 offset:56320
	global_load_lds_dwordx4 v[214:215], off
	s_add_i32 m0, s42, 0x2000
	s_add_u32 s40, s40, 0x100080
	v_lshl_add_u64 v[214:215], v[216:217], 0, s[20:21]
	s_addc_u32 s41, s41, 0
	s_add_i32 s42, s47, s50
	global_load_lds_dwordx4 v[214:215], off
	v_lshl_add_u64 v[214:215], s[40:41], 0, v[162:163]
	s_mov_b32 m0, s42
	s_nop 0
	global_load_lds_dwordx4 v[214:215], off
	v_lshl_add_u64 v[214:215], s[40:41], 0, v[166:167]
	s_add_i32 m0, s42, 0x2000
	s_nop 0
	global_load_lds_dwordx4 v[214:215], off
	v_lshl_add_u64 v[214:215], v[218:219], 0, s[20:21]
	s_mov_b32 m0, s55
	s_nop 0
	global_load_lds_dwordx4 v[214:215], off
	v_lshl_add_u64 v[214:215], v[220:221], 0, s[20:21]
	s_mov_b32 m0, s62
	s_nop 0
	global_load_lds_dwordx4 v[214:215], off
	s_waitcnt vmcnt(8)
	s_waitcnt lgkmcnt(0)
	s_barrier
	s_setprio 1
	s_waitcnt lgkmcnt(0)
	v_mfma_f32_16x16x32_bf16 v[60:63], v[128:131], v[176:179], v[60:63]
	v_mfma_f32_16x16x32_bf16 v[56:59], v[136:139], v[176:179], v[56:59]
	v_mfma_f32_16x16x32_bf16 v[52:55], v[128:131], v[190:193], v[52:55]
	v_mfma_f32_16x16x32_bf16 v[48:51], v[136:139], v[190:193], v[48:51]
	v_mfma_f32_16x16x32_bf16 v[40:43], v[128:131], v[198:201], v[40:43]
	v_mfma_f32_16x16x32_bf16 v[32:35], v[136:139], v[198:201], v[32:35]
	v_mfma_f32_16x16x32_bf16 v[24:27], v[128:131], v[206:209], v[24:27]
	v_mfma_f32_16x16x32_bf16 v[16:19], v[136:139], v[206:209], v[16:19]
	v_mfma_f32_16x16x32_bf16 v[60:63], v[132:135], v[180:183], v[60:63]
	v_mfma_f32_16x16x32_bf16 v[56:59], v[140:143], v[180:183], v[56:59]
	v_mfma_f32_16x16x32_bf16 v[52:55], v[132:135], v[194:197], v[52:55]
	v_mfma_f32_16x16x32_bf16 v[48:51], v[140:143], v[194:197], v[48:51]
	v_mfma_f32_16x16x32_bf16 v[40:43], v[132:135], v[202:205], v[40:43]
	v_mfma_f32_16x16x32_bf16 v[32:35], v[140:143], v[202:205], v[32:35]
	v_mfma_f32_16x16x32_bf16 v[24:27], v[132:135], v[210:213], v[24:27]
	v_mfma_f32_16x16x32_bf16 v[16:19], v[140:143], v[210:213], v[16:19]
	s_setprio 0
	s_setprio 1
	v_mfma_f32_16x16x32_bf16 v[44:47], v[144:147], v[176:179], v[44:47]
	v_mfma_f32_16x16x32_bf16 v[36:39], v[152:155], v[176:179], v[36:39]
	v_mfma_f32_16x16x32_bf16 v[28:31], v[144:147], v[190:193], v[28:31]
	v_mfma_f32_16x16x32_bf16 v[20:23], v[152:155], v[190:193], v[20:23]
	v_mfma_f32_16x16x32_bf16 v[12:15], v[144:147], v[198:201], v[12:15]
	v_mfma_f32_16x16x32_bf16 v[8:11], v[152:155], v[198:201], v[8:11]
	v_mfma_f32_16x16x32_bf16 v[4:7], v[144:147], v[206:209], v[4:7]
	v_mfma_f32_16x16x32_bf16 v[0:3], v[152:155], v[206:209], v[0:3]
	v_mfma_f32_16x16x32_bf16 v[44:47], v[148:151], v[180:183], v[44:47]
	v_mfma_f32_16x16x32_bf16 v[36:39], v[156:159], v[180:183], v[36:39]
	v_mfma_f32_16x16x32_bf16 v[28:31], v[148:151], v[194:197], v[28:31]
	v_mfma_f32_16x16x32_bf16 v[20:23], v[156:159], v[194:197], v[20:23]
	v_mfma_f32_16x16x32_bf16 v[12:15], v[148:151], v[202:205], v[12:15]
	v_mfma_f32_16x16x32_bf16 v[8:11], v[156:159], v[202:205], v[8:11]
	v_mfma_f32_16x16x32_bf16 v[4:7], v[148:151], v[210:213], v[4:7]
	v_mfma_f32_16x16x32_bf16 v[0:3], v[156:159], v[210:213], v[0:3]
	s_setprio 0
	s_barrier
	s_add_i32 s31, s31, 2
	s_add_u32 s38, s38, 0x100
	s_addc_u32 s39, s39, 0
	s_add_u32 s27, s27, 0x100
	s_addc_u32 s29, s29, 0
	s_cmp_gt_u32 s31, 29
	s_cbranch_scc0 .LBB0_1340
	s_and_b64 vcc, exec, s[24:25]
	s_cbranch_vccz .LBB0_1343
	s_barrier
